# lever 7.4: one static s_setprio 1 for waves 4-7 over the whole attention phase, per-cluster flips replaced by s_nop 0 (same wait states)
# baseline (speedup 1.0000x reference)
; #define LAS __attribute__((address_space(3)))
; __device__ __forceinline__ int pi32(int r) { return (r & 0x13) | ((r & 4) << 1) | ((r & 8) >> 1); }
; __device__ __forceinline__ void attn_unit(LAS unsigned char* lds, const bf16_t* Q, const bf16_t* KN, const bf16_t* KPE, const bf16_t* VT, bf16_t* Y, float* ssq_b, int b, int h, int qg) {
;     const int tid = threadIdx.x, wid = __builtin_amdgcn_readfirstlane(tid >> 6), lane = tid & 63, q = lane & 31, hh = lane >> 5;
;     const int t0 = 16 + 256 * qg, c0 = 1 + 4 * qg, cw = c0 + (wid >> 1), ntiles = c0 + 4;
;     bf16x8 qf[12];
;     {
;         const bf16_t* qp = Q + (size_t)(b * 2048 + (t0 - 16) + 32 * wid + q) * 1536 + h * 192 + 8 * hh;
; #pragma unroll
;         for (int ks = 0; ks < 12; ++ks) qf[ks] = *(const bf16x8*)(qp + 16 * ks);
;     }
;     f32x16 o[4];
; #pragma unroll
;     for (int d = 0; d < 4; ++d)
; #pragma unroll
;         for (int i = 0; i < 16; ++i) o[d][i] = 0.f;
;     float mrun = -INFINITY, lsum = 0.f;
;     const char* ksrc[3]; unsigned kstr[3]; const char* vsrc[2];
; #pragma unroll
;     for (int i = 0; i < 3; ++i) {
;         const int s = 64 * (wid * 3 + i) + lane; const int key = s / 24, pos = s - key * 24; const int pc = pos ^ ((key >> 1) & 7);
;         const size_t row = (size_t)b * 2048 + key;
;         if (pc < 16) { ksrc[i] = (const char*)(KN + row * 1024 + h * 128 + pc * 8); kstr[i] = 2048u; }
;         else { ksrc[i] = (const char*)(KPE + row * 64 + (pc - 16) * 8); kstr[i] = 128u; }
;     }
; #pragma unroll
;     for (int i = 0; i < 2; ++i) {
;         const int s = 64 * (wid * 2 + i) + lane; const int d = s >> 3, pos = s & 7; const int pc = pos ^ ((d >> 1) & 7);
;         vsrc[i] = (const char*)(VT + ((size_t)((b * 8 + h) * 128 + d)) * 2048 + pc * 8);
;     }
;     ...
;     const int key0 = pi32(q);
;     const unsigned kbase0 = (unsigned)(key0 * 384) + (unsigned)(((hh ^ ((key0 >> 1) & 7))) << 4);
;     const unsigned vbase0 = (unsigned)(q * 128) + (unsigned)((hh ^ ((q >> 1) & 7)) << 4);
;     AT_DMA(0); __syncthreads();
.LBB0_652:
	v_readfirstlane_b32 s98, v170
	s_nop 3
	s_lshr_b32 s98, s98, 6
	s_cmp_ge_u32 s98, 4
	s_cbranch_scc0 .Lprio_skip_attn
	s_setprio 1
.Lprio_skip_attn:
	s_lshl_b32 s6, s39, 3
	s_and_b32 s6, s6, 56
	s_ashr_i32 s7, s39, 5
	s_add_i32 s6, s6, s7
	s_bfe_u32 s45, s39, 0x20003
	s_ashr_i32 s8, s6, 3
	s_xor_b32 s52, s45, 7
	v_readfirstlane_b32 s53, v170
	s_lshl_b32 s13, s8, 11
	s_lshr_b32 s56, s53, 6
	s_lshl_b32 s28, s52, 8
	v_or_b32_e32 v211, s13, v149
	s_lshl_b32 s12, s56, 5
	v_or_b32_e32 v0, s28, v211
	v_add_u32_e32 v2, s12, v0
	s_waitcnt lgkmcnt(0)
	v_mov_b64_e32 v[0:1], s[60:61]
	s_and_b32 s29, s7, 7
	v_mad_i64_i32 v[0:1], s[6:7], v2, s31, v[0:1]
	s_mul_i32 s6, s29, 0xc0
	s_lshl_b32 s16, s6, 1
	v_lshl_add_u64 v[0:1], v[0:1], 0, s[16:17]
	v_mov_b32_e32 v157, v151
	v_lshl_add_u64 v[0:1], v[0:1], 0, v[156:157]
	global_load_dwordx4 v[140:143], v[0:1], off
	global_load_dwordx4 v[136:139], v[0:1], off offset:32
	global_load_dwordx4 v[132:135], v[0:1], off offset:64
	global_load_dwordx4 v[128:131], v[0:1], off offset:96
	global_load_dwordx4 v[124:127], v[0:1], off offset:128
	global_load_dwordx4 v[120:123], v[0:1], off offset:160
	global_load_dwordx4 v[116:119], v[0:1], off offset:192
	global_load_dwordx4 v[112:115], v[0:1], off offset:224
	global_load_dwordx4 v[108:111], v[0:1], off offset:256
	global_load_dwordx4 v[104:107], v[0:1], off offset:288
	global_load_dwordx4 v[100:103], v[0:1], off offset:320
	global_load_dwordx4 v[96:99], v[0:1], off offset:352
	s_ashr_i32 s9, s8, 31
	s_lshl_b64 s[24:25], s[8:9], 11
	s_mul_i32 s9, s56, 0xc0
	v_or_b32_e32 v0, s9, v144
	v_mul_hi_u32 v2, v0, s34
	v_lshrrev_b32_e32 v150, 4, v2
	v_mad_u64_u32 v[0:1], s[10:11], v150, s35, v[0:1]
	s_lshl_b32 s6, s29, 8
	v_lshrrev_b32_e32 v1, 5, v2
	s_add_u32 s6, s4, s6
	v_bitop3_b32 v0, v0, v1, 7 bitop3:0x78
	s_addc_u32 s7, s5, 0
	v_lshl_add_u64 v[2:3], s[24:25], 0, v[150:151]
	v_cmp_lt_i32_e32 vcc, 15, v0
	v_lshlrev_b32_e32 v0, 3, v0
	s_and_saveexec_b64 s[10:11], vcc
	s_xor_b64 s[10:11], exec, s[10:11]
	v_lshlrev_b64 v[2:3], 7, v[2:3]
	v_lshl_add_u64 v[2:3], s[14:15], 0, v[2:3]
	v_add_u32_e32 v150, 0xffffff80, v0
	v_lshl_add_u64 v[160:161], v[150:151], 1, v[2:3]
	s_or_saveexec_b64 s[10:11], s[10:11]
	v_mov_b64_e32 v[162:163], 0x80
	s_xor_b64 exec, exec, s[10:11]
	v_lshlrev_b64 v[2:3], 11, v[2:3]
	v_lshl_add_u64 v[2:3], s[6:7], 0, v[2:3]
	v_ashrrev_i32_e32 v1, 31, v0
	v_lshl_add_u64 v[160:161], v[0:1], 1, v[2:3]
	v_mov_b64_e32 v[162:163], 0x800
	s_or_b64 exec, exec, s[10:11]
	s_mul_i32 s64, s56, 3
	s_add_i32 s57, s64, 1
	v_lshl_or_b32 v0, s57, 6, v144
	v_mul_hi_u32 v2, v0, s36
	v_lshrrev_b32_e32 v150, 2, v2
	v_mad_u64_u32 v[0:1], s[10:11], v150, s35, v[0:1]
	v_lshrrev_b32_e32 v1, 3, v2
	v_bitop3_b32 v0, v0, v1, 7 bitop3:0x78
	v_lshl_add_u64 v[2:3], s[24:25], 0, v[150:151]
	v_cmp_lt_i32_e32 vcc, 15, v0
	v_lshlrev_b32_e32 v0, 3, v0
	s_and_saveexec_b64 s[10:11], vcc
	s_xor_b64 s[10:11], exec, s[10:11]
	v_lshlrev_b64 v[2:3], 7, v[2:3]
	v_lshl_add_u64 v[2:3], s[14:15], 0, v[2:3]
	v_add_u32_e32 v150, 0xffffff80, v0
	v_lshl_add_u64 v[164:165], v[150:151], 1, v[2:3]
	s_or_saveexec_b64 s[10:11], s[10:11]
	v_mov_b64_e32 v[166:167], 0x80
	s_xor_b64 exec, exec, s[10:11]
	v_lshlrev_b64 v[2:3], 11, v[2:3]
	v_lshl_add_u64 v[2:3], s[6:7], 0, v[2:3]
	v_ashrrev_i32_e32 v1, 31, v0
	v_lshl_add_u64 v[164:165], v[0:1], 1, v[2:3]
	v_mov_b64_e32 v[166:167], 0x800
	s_or_b64 exec, exec, s[10:11]
	s_add_i32 s64, s64, 2
	v_lshl_or_b32 v0, s64, 6, v144
	v_mul_hi_u32 v2, v0, s36
	v_lshrrev_b32_e32 v150, 2, v2
	v_mad_u64_u32 v[0:1], s[10:11], v150, s35, v[0:1]
	v_lshrrev_b32_e32 v1, 3, v2
	v_bitop3_b32 v0, v0, v1, 7 bitop3:0x78
	v_lshl_add_u64 v[2:3], s[24:25], 0, v[150:151]
	v_cmp_lt_i32_e32 vcc, 15, v0
	v_lshlrev_b32_e32 v0, 3, v0
	s_and_saveexec_b64 s[10:11], vcc
	s_xor_b64 s[10:11], exec, s[10:11]
	v_lshlrev_b64 v[2:3], 7, v[2:3]
	v_lshl_add_u64 v[2:3], s[14:15], 0, v[2:3]
	v_add_u32_e32 v150, 0xffffff80, v0
	v_lshl_add_u64 v[168:169], v[150:151], 1, v[2:3]
	s_or_saveexec_b64 s[10:11], s[10:11]
	s_lshl_b32 s29, s29, 7
	v_mov_b64_e32 v[176:177], 0x80
	s_xor_b64 exec, exec, s[10:11]
	v_lshlrev_b64 v[2:3], 11, v[2:3]
	v_lshl_add_u64 v[2:3], s[6:7], 0, v[2:3]
	v_ashrrev_i32_e32 v1, 31, v0
	v_lshl_add_u64 v[168:169], v[0:1], 1, v[2:3]
	v_mov_b64_e32 v[176:177], 0x800
	s_or_b64 exec, exec, s[10:11]
	v_lshl_or_b32 v2, s56, 7, v144
	s_lshl_b32 s44, s8, 10
	s_or_b32 s54, s44, s29
	v_ashrrev_i32_e32 v0, 3, v2
	v_add_u32_e32 v0, s54, v0
	v_ashrrev_i32_e32 v1, 31, v0
	v_lshlrev_b64 v[64:65], 12, v[0:1]
	v_or_b32_e32 v0, 64, v2
	v_ashrrev_i32_e32 v1, 3, v0
	v_lshrrev_b32_e32 v77, 4, v0
	v_add_u32_e32 v0, s54, v1
	v_xor_b32_e32 v2, v77, v170
	v_ashrrev_i32_e32 v1, 31, v0
	v_lshlrev_b64 v[66:67], 12, v[0:1]
	v_lshlrev_b32_e32 v2, 4, v2
	v_lshl_add_u64 v[0:1], s[42:43], 0, v[66:67]
	v_and_b32_e32 v150, 0x70, v2
	s_sub_i32 s55, 0x4000, s13
	v_lshl_add_u64 v[180:181], v[0:1], 0, v[150:151]
	s_sub_i32 s10, 8, s8
	v_mad_u64_u32 v[0:1], s[8:9], v162, s55, v[160:161]
	s_mul_i32 s9, s56, 0xc00
	s_add_i32 s8, s9, 0
	s_lshl_b32 s13, s57, 10
	s_mov_b32 m0, s8
	s_add_i32 s50, s13, 0
	s_lshl_b32 s57, s64, 10
	s_mov_b32 s11, s17
	global_load_lds_dwordx4 v[0:1], off
	v_mad_u64_u32 v[0:1], s[66:67], v166, s55, v[164:165]
	s_mov_b32 m0, s50
	s_add_i32 s51, s57, 0
	s_lshl_b32 s64, s56, 11
	v_lshl_add_u64 v[178:179], v[152:153], 0, v[64:65]
	global_load_lds_dwordx4 v[0:1], off
	v_mad_u64_u32 v[0:1], s[66:67], v176, s55, v[168:169]
	s_mov_b32 m0, s51
	s_lshl_b64 s[10:11], s[10:11], 22
	s_add_i32 s56, s64, 0
	global_load_lds_dwordx4 v[0:1], off
	s_add_i32 m0, s56, 0x6000
	v_lshl_add_u64 v[0:1], v[178:179], 0, s[10:11]
	global_load_lds_dwordx4 v[0:1], off
	v_lshl_add_u64 v[0:1], v[180:181], 0, s[10:11]
	s_add_i32 m0, s56, 0x6400
	s_lshl_b32 s66, s52, 2
	global_load_lds_dwordx4 v[0:1], off
	s_add_i32 m0, s8, 0xa000
	s_waitcnt vmcnt(0) lgkmcnt(0)
	s_barrier
; __device__ __forceinline__ void attn_unit(LAS unsigned char* lds, const bf16_t* Q, const bf16_t* KN, const bf16_t* KPE, const bf16_t* VT, bf16_t* Y, float* ssq_b, int b, int h, int qg) {
;     ...
;         if (j + 1 < ntiles) AT_DMA(j + 1);
;         if (j <= cw) {
;             const LAS unsigned char* kb = lds + (j & 1) * KV_BYTES; const LAS unsigned char* vb = kb + KS_BYTES;
;             f32x16 s0, s1;
; #pragma unroll
;             for (int i = 0; i < 16; ++i) { s0[i] = 0.f; s1[i] = 0.f; }
;             __builtin_amdgcn_s_setprio(1);
;             {
;                 bf16x8 a0n = *(const LAS bf16x8*)(kb + kbase0), a1n = *(const LAS bf16x8*)(kb + (kbase0 + 32u * 384u));
; #pragma unroll
;                 for (int ks = 0; ks < 12; ++ks) {
;                     const bf16x8 a0 = a0n, a1 = a1n;
;                     if (ks + 1 < 12) { const unsigned off = (kbase0 ^ (unsigned)(((2 * (ks + 1)) & 7) << 4)) + (unsigned)(((2 * (ks + 1)) & 24) << 4);
;                         a0n = *(const LAS bf16x8*)(kb + off); a1n = *(const LAS bf16x8*)(kb + (off + 32u * 384u)); }
;                     s0 = __builtin_amdgcn_mfma_f32_32x32x16_bf16(a0, qf[ks], s0, 0, 0, 0);
;                     s1 = __builtin_amdgcn_mfma_f32_32x32x16_bf16(a1, qf[ks], s1, 0, 0, 0);
;                 }
;             }
;             __builtin_amdgcn_s_setprio(0);
;             if (j == 0) {
; #pragma unroll
;                 for (int i = 0; i < 16; ++i) { if (i >= 8) s0[i] = -INFINITY; s1[i] = -INFINITY; }
;             }
;             float mx = s0[0];
; #pragma unroll
;             for (int i = 1; i < 16; ++i) mx = fmaxf(mx, s0[i]);
; #pragma unroll
;             for (int i = 0; i < 16; ++i) mx = fmaxf(mx, s1[i]);
;             mx = fmaxf(mx, __shfl_xor(mx, 32));
;             const bool upd = __builtin_amdgcn_ballot_w64(mx - mrun > 8.0f) != 0ull;
;             const float mn = upd ? fmaxf(mrun, mx) : mrun; const float alpha = upd ? fexp2(mrun - mn) : 1.0f; mrun = mn;
;             s0 = s0 - mn; s1 = s1 - mn;
; #pragma unroll
;             for (int i = 0; i < 16; ++i) { s0[i] = fexp2(s0[i]); s1[i] = fexp2(s1[i]); }
;             const f32x16 t16 = s0 + s1;
;             typedef float f32x8_ __attribute__((ext_vector_type(8)));
;             const f32x8_ t8 = __builtin_shufflevector(t16, t16, 0, 1, 2, 3, 4, 5, 6, 7) + __builtin_shufflevector(t16, t16, 8, 9, 10, 11, 12, 13, 14, 15);
	global_load_lds_dwordx4 v[160:161], off
	s_add_i32 m0, s50, 0xa000
	s_lshr_b32 s8, s53, 7
	global_load_lds_dwordx4 v[164:165], off
	s_add_i32 m0, s51, 0xa000
	s_add_i32 s65, s8, s66
	global_load_lds_dwordx4 v[168:169], off
	s_add_i32 m0, s56, 0x10000
	s_add_i32 s65, s65, 1
	global_load_lds_dwordx4 v[178:179], off
	s_add_i32 m0, s56, 0x10400
	s_lshr_b32 s56, s39, 3
	global_load_lds_dwordx4 v[180:181], off
	s_nop 0
	v_add_u32_e32 v209, 0, v197
	v_add_u32_e32 v210, 0, v199
	v_add_u32_e32 v208, 0, v200
	v_add_u32_e32 v207, 0, v201
	ds_read_b128 v[0:3], v209
	ds_read_b128 v[16:19], v210
	ds_read_b128 v[20:23], v208
	ds_read_b128 v[24:27], v207
	ds_read_b128 v[28:31], v209 offset:128
	ds_read_b128 v[32:35], v210 offset:128
	ds_read_b128 v[36:39], v208 offset:128
	ds_read_b128 v[40:43], v207 offset:128
	ds_read_b128 v[44:47], v209 offset:256
	ds_read_b128 v[48:51], v210 offset:256
	ds_read_b128 v[52:55], v208 offset:256
	ds_read_b128 v[56:59], v207 offset:256
	s_waitcnt lgkmcnt(11)
	v_mfma_f32_32x32x16_bf16 v[0:15], v[0:3], v[140:143], 0
	s_waitcnt lgkmcnt(10)
	v_mfma_f32_32x32x16_bf16 v[0:15], v[16:19], v[136:139], v[0:15]
	s_waitcnt lgkmcnt(9)
	v_mfma_f32_32x32x16_bf16 v[0:15], v[20:23], v[132:135], v[0:15]
	s_waitcnt lgkmcnt(8)
	v_mfma_f32_32x32x16_bf16 v[0:15], v[24:27], v[128:131], v[0:15]
	s_waitcnt lgkmcnt(7)
	v_mfma_f32_32x32x16_bf16 v[0:15], v[28:31], v[124:127], v[0:15]
	s_waitcnt lgkmcnt(6)
	v_mfma_f32_32x32x16_bf16 v[0:15], v[32:35], v[120:123], v[0:15]
	s_waitcnt lgkmcnt(5)
	v_mfma_f32_32x32x16_bf16 v[0:15], v[36:39], v[116:119], v[0:15]
	s_waitcnt lgkmcnt(4)
	v_mfma_f32_32x32x16_bf16 v[0:15], v[40:43], v[112:115], v[0:15]
	s_waitcnt lgkmcnt(3)
	v_mfma_f32_32x32x16_bf16 v[0:15], v[44:47], v[108:111], v[0:15]
	s_waitcnt lgkmcnt(2)
	v_mfma_f32_32x32x16_bf16 v[0:15], v[48:51], v[104:107], v[0:15]
	s_waitcnt lgkmcnt(1)
	v_mfma_f32_32x32x16_bf16 v[0:15], v[52:55], v[100:103], v[0:15]
	s_waitcnt lgkmcnt(0)
	v_mfma_f32_32x32x16_bf16 v[0:15], v[56:59], v[96:99], v[0:15]
	s_nop 0
	s_nop 10
	v_max3_f32 v8, v0, v1, v2
	v_max3_f32 v8, v8, v3, v4
	v_max3_f32 v8, v8, v5, v6
	v_max3_f32 v8, v8, v7, s37
	ds_bpermute_b32 v9, v205, v8
	s_waitcnt lgkmcnt(0)
	v_max_f32_e32 v9, v9, v9
	v_max_f32_e32 v8, v8, v9
	v_add_f32_e32 v9, 0x7f800000, v8
	v_cmp_lt_f32_e32 vcc, s38, v9
	s_cmp_eq_u64 vcc, 0
	v_max_f32_e32 v8, 0xff800000, v8
	s_cselect_b64 vcc, -1, 0
	v_cndmask_b32_e32 v163, v8, v206, vcc
	v_sub_f32_e32 v8, 0xff800000, v163
	v_sub_f32_e32 v7, v7, v163
	v_sub_f32_e32 v6, v6, v163
	v_sub_f32_e32 v5, v5, v163
	v_sub_f32_e32 v4, v4, v163
	v_sub_f32_e32 v3, v3, v163
	v_sub_f32_e32 v2, v2, v163
	v_sub_f32_e32 v1, v1, v163
	v_sub_f32_e32 v0, v0, v163
	v_exp_f32_e32 v76, v8
	v_exp_f32_e32 v16, v0
	v_exp_f32_e32 v17, v1
	v_exp_f32_e32 v18, v2
	v_exp_f32_e32 v19, v3
	v_exp_f32_e32 v20, v6
	v_exp_f32_e32 v21, v7
	v_exp_f32_e32 v22, v4
	v_exp_f32_e32 v23, v5
	v_pk_add_f32 v[0:1], v[76:77], v[18:19] op_sel_hi:[0,1]
	v_pk_add_f32 v[2:3], v[76:77], v[20:21] op_sel_hi:[0,1]
	v_pk_add_f32 v[4:5], v[76:77], v[16:17] op_sel_hi:[0,1]
	v_pk_add_f32 v[6:7], v[76:77], v[22:23] op_sel_hi:[0,1]
	v_pk_fma_f32 v[6:7], v[76:77], 2.0, v[6:7] op_sel_hi:[0,0,1]
	v_pk_fma_f32 v[4:5], v[76:77], 2.0, v[4:5] op_sel_hi:[0,0,1]
	v_pk_fma_f32 v[2:3], v[76:77], 2.0, v[2:3] op_sel_hi:[0,0,1]
	v_pk_fma_f32 v[0:1], v[76:77], 2.0, v[0:1] op_sel_hi:[0,0,1]
	v_pk_add_f32 v[0:1], v[0:1], v[2:3]
	v_pk_add_f32 v[2:3], v[4:5], v[6:7]
	v_cvt_pk_bf16_f32 v68, v16, v17
	v_cvt_pk_bf16_f32 v69, v18, v19
	v_cvt_pk_bf16_f32 v70, v22, v23
	v_cvt_pk_bf16_f32 v71, v20, v21
	s_nop 0
	v_pk_mov_b32 v[4:5], v[2:3], v[0:1] op_sel:[1,0]
	v_mov_b32_e32 v3, v1
	v_pk_add_f32 v[0:1], v[4:5], v[2:3]
	s_nop 0
	v_add_f32_e32 v1, v0, v1
	v_mul_f32_e32 v0, 0, v76
	v_cndmask_b32_e64 v0, v0, 0, vcc
	v_add_f32_e32 v157, v0, v1
	v_mov_b32_e32 v1, v0
	v_mov_b32_e32 v2, v0
	v_mov_b32_e32 v3, v0
	v_mov_b32_e32 v4, v0
	v_mov_b32_e32 v5, v0
	v_mov_b32_e32 v6, v0
	v_mov_b32_e32 v7, v0
	v_mov_b32_e32 v8, v0
	v_mov_b32_e32 v9, v0
	v_mov_b32_e32 v10, v0
	v_mov_b32_e32 v11, v0
	v_mov_b32_e32 v12, v0
	v_mov_b32_e32 v13, v0
	v_mov_b32_e32 v14, v0
	v_mov_b32_e32 v15, v0
	s_nop 0
	v_add_u32_e32 v215, 0, v198
	ds_read_b128 v[16:19], v215 offset:24576
	ds_read_b128 v[72:75], v215 offset:32768
	s_waitcnt lgkmcnt(0)
	v_mfma_f32_32x32x16_bf16 v[48:63], v[16:19], v[68:71], v[0:15]
	ds_read_b128 v[16:19], v215 offset:28672
	s_waitcnt lgkmcnt(0)
	v_mfma_f32_32x32x16_bf16 v[32:47], v[16:19], v[68:71], v[0:15]
	v_mfma_f32_32x32x16_bf16 v[16:31], v[72:75], v[68:71], v[0:15]
	ds_read_b128 v[72:75], v215 offset:36864
	s_waitcnt lgkmcnt(0)
	v_mfma_f32_32x32x16_bf16 v[0:15], v[72:75], v[68:71], v[0:15]
	s_nop 0
	v_add_u32_e32 v213, 0, v202
	v_add_u32_e32 v214, 0, v203
	v_add_u32_e32 v216, 0, v204
	v_lshl_add_u64 v[182:183], v[154:155], 0, v[64:65]
	v_bitop3_b32 v64, v77, 7, v170 bitop3:0x48
	v_lshl_or_b32 v66, v64, 4, v66
	v_lshlrev_b32_e32 v150, 6, v176
	v_lshlrev_b32_e32 v188, 6, v166
	v_mov_b32_e32 v189, v151
	v_lshlrev_b32_e32 v192, 6, v162
	v_mov_b32_e32 v193, v151
	v_lshl_add_u64 v[184:185], s[18:19], 0, v[66:67]
	v_lshl_add_u64 v[186:187], v[168:169], 0, v[150:151]
	v_lshl_add_u64 v[190:191], v[164:165], 0, v[188:189]
	v_lshl_add_u64 v[194:195], v[160:161], 0, v[192:193]
	s_mov_b32 s67, -3
	s_waitcnt vmcnt(0)
	s_barrier
; __device__ __forceinline__ void attn_unit(LAS unsigned char* lds, const bf16_t* Q, const bf16_t* KN, const bf16_t* KPE, const bf16_t* VT, bf16_t* Y, float* ssq_b, int b, int h, int qg) {
;     ...
;         if (j + 1 < ntiles) AT_DMA(j + 1);
;         if (j <= cw) {
;             const LAS unsigned char* kb = lds + (j & 1) * KV_BYTES; const LAS unsigned char* vb = kb + KS_BYTES;
;             f32x16 s0, s1;
; #pragma unroll
;             for (int i = 0; i < 16; ++i) { s0[i] = 0.f; s1[i] = 0.f; }
;             __builtin_amdgcn_s_setprio(1);
;             {
;                 bf16x8 a0n = *(const LAS bf16x8*)(kb + kbase0), a1n = *(const LAS bf16x8*)(kb + (kbase0 + 32u * 384u));
; #pragma unroll
;                 for (int ks = 0; ks < 12; ++ks) {
;                     const bf16x8 a0 = a0n, a1 = a1n;
;                     if (ks + 1 < 12) { const unsigned off = (kbase0 ^ (unsigned)(((2 * (ks + 1)) & 7) << 4)) + (unsigned)(((2 * (ks + 1)) & 24) << 4);
;                         a0n = *(const LAS bf16x8*)(kb + off); a1n = *(const LAS bf16x8*)(kb + (off + 32u * 384u)); }
;                     s0 = __builtin_amdgcn_mfma_f32_32x32x16_bf16(a0, qf[ks], s0, 0, 0, 0);
;                     s1 = __builtin_amdgcn_mfma_f32_32x32x16_bf16(a1, qf[ks], s1, 0, 0, 0);
;                 }
;             }
;             __builtin_amdgcn_s_setprio(0);
;             if (j == 0) {
; #pragma unroll
;                 for (int i = 0; i < 16; ++i) { if (i >= 8) s0[i] = -INFINITY; s1[i] = -INFINITY; }
;             }
;             float mx = s0[0];
; #pragma unroll
;             for (int i = 1; i < 16; ++i) mx = fmaxf(mx, s0[i]);
; #pragma unroll
;             for (int i = 0; i < 16; ++i) mx = fmaxf(mx, s1[i]);
;             mx = fmaxf(mx, __shfl_xor(mx, 32));
;             const bool upd = __builtin_amdgcn_ballot_w64(mx - mrun > 8.0f) != 0ull;
;             const float mn = upd ? fmaxf(mrun, mx) : mrun; const float alpha = upd ? fexp2(mrun - mn) : 1.0f; mrun = mn;
;             s0 = s0 - mn; s1 = s1 - mn;
; #pragma unroll
;             for (int i = 0; i < 16; ++i) { s0[i] = fexp2(s0[i]); s1[i] = fexp2(s1[i]); }
;             const f32x16 t16 = s0 + s1;
;             typedef float f32x8_ __attribute__((ext_vector_type(8)));
;             const f32x8_ t8 = __builtin_shufflevector(t16, t16, 0, 1, 2, 3, 4, 5, 6, 7) + __builtin_shufflevector(t16, t16, 8, 9, 10, 11, 12, 13, 14, 15);
.LBB0_665:
	s_add_i32 s52, s67, 4
	s_bitcmp1_b32 s67, 0
	s_cselect_b32 s8, 0, 0xa000
	s_add_i32 s8, s8, 0
	s_add_i32 m0, s8, s9
	s_add_i32 s50, s8, s64
	global_load_lds_dwordx4 v[194:195], off
	s_add_i32 m0, s8, s13
	s_nop 0
	global_load_lds_dwordx4 v[190:191], off
	s_add_i32 m0, s8, s57
	s_nop 0
	global_load_lds_dwordx4 v[186:187], off
	s_add_i32 m0, s50, 0x6000
	s_nop 0
	global_load_lds_dwordx4 v[182:183], off
	s_add_i32 m0, s50, 0x6400
	s_cmp_gt_u32 s52, s65
	global_load_lds_dwordx4 v[184:185], off
	s_cbranch_scc1 .LBB0_669
	s_bitcmp1_b32 s52, 0
	s_cselect_b32 s50, 0xa000, 0
	s_add_i32 s68, s50, 0
	s_nop 0
	v_add_u32_e32 v159, s68, v197
	v_add_u32_e32 v167, s68, v199
	v_add_u32_e32 v177, s68, v200
	v_add_u32_e32 v196, s68, v201
	ds_read_b128 v[218:221], v159
	ds_read_b128 v[222:225], v159 offset:12288
	ds_read_b128 v[226:229], v167
	ds_read_b128 v[230:233], v167 offset:12288
	ds_read_b128 v[244:247], v177
	ds_read_b128 v[248:251], v177 offset:12288
	s_waitcnt lgkmcnt(4)
	v_mfma_f32_32x32x16_bf16 v[80:95], v[218:221], v[140:143], 0
	v_mfma_f32_32x32x16_bf16 v[64:79], v[222:225], v[140:143], 0
	ds_read_b128 v[218:221], v196
	ds_read_b128 v[222:225], v196 offset:12288
	s_waitcnt lgkmcnt(4)
	v_mfma_f32_32x32x16_bf16 v[80:95], v[226:229], v[136:139], v[80:95]
	v_mfma_f32_32x32x16_bf16 v[64:79], v[230:233], v[136:139], v[64:79]
	ds_read_b128 v[226:229], v159 offset:128
	ds_read_b128 v[230:233], v159 offset:12416
	s_waitcnt lgkmcnt(4)
	v_mfma_f32_32x32x16_bf16 v[80:95], v[244:247], v[132:135], v[80:95]
	v_mfma_f32_32x32x16_bf16 v[64:79], v[248:251], v[132:135], v[64:79]
	ds_read_b128 v[244:247], v167 offset:128
	ds_read_b128 v[248:251], v167 offset:12416
	s_waitcnt lgkmcnt(4)
	v_mfma_f32_32x32x16_bf16 v[80:95], v[218:221], v[128:131], v[80:95]
	v_mfma_f32_32x32x16_bf16 v[64:79], v[222:225], v[128:131], v[64:79]
	ds_read_b128 v[218:221], v177 offset:128
	ds_read_b128 v[222:225], v177 offset:12416
	s_waitcnt lgkmcnt(4)
	v_mfma_f32_32x32x16_bf16 v[80:95], v[226:229], v[124:127], v[80:95]
	v_mfma_f32_32x32x16_bf16 v[64:79], v[230:233], v[124:127], v[64:79]
	ds_read_b128 v[226:229], v196 offset:128
	ds_read_b128 v[230:233], v196 offset:12416
	s_waitcnt lgkmcnt(4)
	v_mfma_f32_32x32x16_bf16 v[80:95], v[244:247], v[120:123], v[80:95]
	v_mfma_f32_32x32x16_bf16 v[64:79], v[248:251], v[120:123], v[64:79]
	ds_read_b128 v[244:247], v159 offset:256
	ds_read_b128 v[248:251], v159 offset:12544
	s_waitcnt lgkmcnt(4)
	v_mfma_f32_32x32x16_bf16 v[80:95], v[218:221], v[116:119], v[80:95]
	v_mfma_f32_32x32x16_bf16 v[64:79], v[222:225], v[116:119], v[64:79]
	ds_read_b128 v[218:221], v167 offset:256
	ds_read_b128 v[222:225], v167 offset:12544
	s_waitcnt lgkmcnt(4)
	v_mfma_f32_32x32x16_bf16 v[80:95], v[226:229], v[112:115], v[80:95]
	v_mfma_f32_32x32x16_bf16 v[64:79], v[230:233], v[112:115], v[64:79]
	ds_read_b128 v[226:229], v177 offset:256
	ds_read_b128 v[230:233], v177 offset:12544
	s_waitcnt lgkmcnt(4)
	v_mfma_f32_32x32x16_bf16 v[80:95], v[244:247], v[108:111], v[80:95]
	v_mfma_f32_32x32x16_bf16 v[64:79], v[248:251], v[108:111], v[64:79]
	ds_read_b128 v[244:247], v196 offset:256
	ds_read_b128 v[248:251], v196 offset:12544
	s_waitcnt lgkmcnt(4)
	v_mfma_f32_32x32x16_bf16 v[80:95], v[218:221], v[104:107], v[80:95]
	v_mfma_f32_32x32x16_bf16 v[64:79], v[222:225], v[104:107], v[64:79]
	s_waitcnt lgkmcnt(2)
	v_mfma_f32_32x32x16_bf16 v[80:95], v[226:229], v[100:103], v[80:95]
	v_mfma_f32_32x32x16_bf16 v[64:79], v[230:233], v[100:103], v[64:79]
	s_waitcnt lgkmcnt(0)
	v_mfma_f32_32x32x16_bf16 v[80:95], v[244:247], v[96:99], v[80:95]
	v_mfma_f32_32x32x16_bf16 v[64:79], v[248:251], v[96:99], v[64:79]
	v_add_u32_e32 v252, s68, v198
	v_add_u32_e32 v253, s68, v202
	v_add_u32_e32 v254, s68, v203
	v_add_u32_e32 v255, s68, v204
	ds_read_b128 v[244:247], v252 offset:24576
	ds_read_b128 v[248:251], v252 offset:28672
	s_nop 0
	s_nop 7
	v_max_f32_e32 v159, v81, v81
	v_max_f32_e32 v167, v80, v80
	v_max_f32_e32 v159, v167, v159
	v_max3_f32 v159, v159, v82, v83
	v_max3_f32 v159, v159, v84, v85
	v_max3_f32 v159, v159, v86, v87
	v_max3_f32 v159, v159, v88, v89
	v_max3_f32 v159, v159, v90, v91
	v_max3_f32 v159, v159, v92, v93
	v_max3_f32 v159, v159, v94, v95
	v_max3_f32 v159, v159, v64, v65
	v_max3_f32 v159, v159, v66, v67
	v_max3_f32 v159, v159, v68, v69
	v_max3_f32 v159, v159, v70, v71
	v_max3_f32 v159, v159, v72, v73
	v_max3_f32 v159, v159, v74, v75
	v_max3_f32 v159, v159, v76, v77
	v_max3_f32 v159, v159, v78, v79
	ds_bpermute_b32 v167, v205, v159
	s_waitcnt lgkmcnt(0)
	v_max_f32_e32 v167, v167, v167
	v_max_f32_e32 v159, v159, v167
	v_sub_f32_e32 v167, v159, v163
	v_cmp_lt_f32_e32 vcc, s38, v167
	s_cmp_eq_u64 vcc, 0
	v_max_f32_e32 v167, v163, v163
	s_cselect_b64 s[52:53], -1, 0
	v_max_f32_e32 v159, v167, v159
	v_cndmask_b32_e64 v159, v159, v163, s[52:53]
	v_sub_f32_e32 v163, v163, v159
	v_exp_f32_e32 v196, v163
	s_cbranch_vccz .LBB0_668
	v_pk_mul_f32 v[62:63], v[62:63], v[196:197] op_sel_hi:[1,0]
	v_pk_mul_f32 v[60:61], v[60:61], v[196:197] op_sel_hi:[1,0]
	v_pk_mul_f32 v[58:59], v[58:59], v[196:197] op_sel_hi:[1,0]
	v_pk_mul_f32 v[56:57], v[56:57], v[196:197] op_sel_hi:[1,0]
	v_pk_mul_f32 v[54:55], v[54:55], v[196:197] op_sel_hi:[1,0]
	v_pk_mul_f32 v[52:53], v[52:53], v[196:197] op_sel_hi:[1,0]
	v_pk_mul_f32 v[50:51], v[50:51], v[196:197] op_sel_hi:[1,0]
	v_pk_mul_f32 v[48:49], v[48:49], v[196:197] op_sel_hi:[1,0]
	v_pk_mul_f32 v[46:47], v[46:47], v[196:197] op_sel_hi:[1,0]
	v_pk_mul_f32 v[44:45], v[44:45], v[196:197] op_sel_hi:[1,0]
	v_pk_mul_f32 v[42:43], v[42:43], v[196:197] op_sel_hi:[1,0]
	v_pk_mul_f32 v[40:41], v[40:41], v[196:197] op_sel_hi:[1,0]
	v_pk_mul_f32 v[38:39], v[38:39], v[196:197] op_sel_hi:[1,0]
	v_pk_mul_f32 v[36:37], v[36:37], v[196:197] op_sel_hi:[1,0]
	v_pk_mul_f32 v[34:35], v[34:35], v[196:197] op_sel_hi:[1,0]
	v_pk_mul_f32 v[32:33], v[32:33], v[196:197] op_sel_hi:[1,0]
	v_pk_mul_f32 v[30:31], v[30:31], v[196:197] op_sel_hi:[1,0]
	v_pk_mul_f32 v[28:29], v[28:29], v[196:197] op_sel_hi:[1,0]
	v_pk_mul_f32 v[26:27], v[26:27], v[196:197] op_sel_hi:[1,0]
	v_pk_mul_f32 v[24:25], v[24:25], v[196:197] op_sel_hi:[1,0]
	v_pk_mul_f32 v[22:23], v[22:23], v[196:197] op_sel_hi:[1,0]
	v_pk_mul_f32 v[20:21], v[20:21], v[196:197] op_sel_hi:[1,0]
	v_pk_mul_f32 v[18:19], v[18:19], v[196:197] op_sel_hi:[1,0]
	v_pk_mul_f32 v[16:17], v[16:17], v[196:197] op_sel_hi:[1,0]
	v_pk_mul_f32 v[14:15], v[14:15], v[196:197] op_sel_hi:[1,0]
	v_pk_mul_f32 v[12:13], v[12:13], v[196:197] op_sel_hi:[1,0]
	v_pk_mul_f32 v[10:11], v[10:11], v[196:197] op_sel_hi:[1,0]
	v_pk_mul_f32 v[8:9], v[8:9], v[196:197] op_sel_hi:[1,0]
	v_pk_mul_f32 v[6:7], v[6:7], v[196:197] op_sel_hi:[1,0]
	v_pk_mul_f32 v[4:5], v[4:5], v[196:197] op_sel_hi:[1,0]
	v_pk_mul_f32 v[2:3], v[2:3], v[196:197] op_sel_hi:[1,0]
	v_pk_mul_f32 v[0:1], v[0:1], v[196:197] op_sel_hi:[1,0]
; #define LAS __attribute__((address_space(3)))
; __device__ __forceinline__ void attn_unit(LAS unsigned char* lds, const bf16_t* Q, const bf16_t* KN, const bf16_t* KPE, const bf16_t* VT, bf16_t* Y, float* ssq_b, int b, int h, int qg) {
;     ...
;             const float mn = upd ? fmaxf(mrun, mx) : mrun; const float alpha = upd ? fexp2(mrun - mn) : 1.0f; mrun = mn;
;             s0 = s0 - mn; s1 = s1 - mn;
; #pragma unroll
;             for (int i = 0; i < 16; ++i) { s0[i] = fexp2(s0[i]); s1[i] = fexp2(s1[i]); }
;             const f32x16 t16 = s0 + s1;
;             typedef float f32x8_ __attribute__((ext_vector_type(8)));
;             const f32x8_ t8 = __builtin_shufflevector(t16, t16, 0, 1, 2, 3, 4, 5, 6, 7) + __builtin_shufflevector(t16, t16, 8, 9, 10, 11, 12, 13, 14, 15);
;             const f32x4 t4 = __builtin_shufflevector(t8, t8, 0, 1, 2, 3) + __builtin_shufflevector(t8, t8, 4, 5, 6, 7);
;             const float ps = (t4[0] + t4[1]) + (t4[2] + t4[3]);
;             lsum = lsum * alpha + ps;
;             if (upd) {
; #pragma unroll
;                 for (int d = 0; d < 4; ++d)
; #pragma unroll
;                     for (int i = 0; i < 16; ++i) o[d][i] *= alpha;
;             }
; #pragma unroll
;             for (int kb2 = 0; kb2 < 2; ++kb2)
; #pragma unroll
;                 for (int a = 0; a < 2; ++a) {
;                     u32x4 pw;
;                     if (kb2 == 0) { pw.x = cvt_pk(s0[8 * a + 0], s0[8 * a + 1]); pw.y = cvt_pk(s0[8 * a + 2], s0[8 * a + 3]); pw.z = cvt_pk(s0[8 * a + 4], s0[8 * a + 5]); pw.w = cvt_pk(s0[8 * a + 6], s0[8 * a + 7]); }
;                     else { pw.x = cvt_pk(s1[8 * a + 0], s1[8 * a + 1]); pw.y = cvt_pk(s1[8 * a + 2], s1[8 * a + 3]); pw.z = cvt_pk(s1[8 * a + 4], s1[8 * a + 5]); pw.w = cvt_pk(s1[8 * a + 6], s1[8 * a + 7]); }
;                     const bf16x8 pf = __builtin_bit_cast(bf16x8, pw);
;                     const unsigned vro = vbase0 ^ (unsigned)((4 * kb2 + 2 * a) << 4);
;                     __builtin_amdgcn_s_setprio(1);
; #pragma unroll
;                     for (int db = 0; db < 4; ++db) {
;                         const bf16x8 vf = *(const LAS bf16x8*)(vb + (vro + (unsigned)(db * 4096)));
;                         o[db] = __builtin_amdgcn_mfma_f32_32x32x16_bf16(vf, pf, o[db], 0, 0, 0);
;                     }
;                     __builtin_amdgcn_s_setprio(0);
;                 }
.LBB0_668:
	v_sub_f32_e32 v95, v95, v159
	v_sub_f32_e32 v94, v94, v159
	v_sub_f32_e32 v93, v93, v159
	v_sub_f32_e32 v92, v92, v159
	v_sub_f32_e32 v91, v91, v159
	v_sub_f32_e32 v90, v90, v159
	v_sub_f32_e32 v89, v89, v159
	v_sub_f32_e32 v88, v88, v159
	v_sub_f32_e32 v87, v87, v159
	v_sub_f32_e32 v86, v86, v159
	v_sub_f32_e32 v85, v85, v159
	v_sub_f32_e32 v84, v84, v159
	v_sub_f32_e32 v83, v83, v159
	v_sub_f32_e32 v82, v82, v159
	v_sub_f32_e32 v81, v81, v159
	v_sub_f32_e32 v80, v80, v159
	v_sub_f32_e32 v163, v79, v159
	v_sub_f32_e32 v167, v78, v159
	v_sub_f32_e32 v177, v77, v159
	v_sub_f32_e32 v217, v76, v159
	v_sub_f32_e32 v218, v75, v159
	v_sub_f32_e32 v219, v74, v159
	v_sub_f32_e32 v220, v73, v159
	v_sub_f32_e32 v221, v72, v159
	v_sub_f32_e32 v79, v71, v159
	v_sub_f32_e32 v71, v70, v159
	v_sub_f32_e32 v70, v69, v159
	v_sub_f32_e32 v69, v68, v159
	v_sub_f32_e32 v68, v67, v159
	v_sub_f32_e32 v67, v66, v159
	v_sub_f32_e32 v66, v65, v159
	v_sub_f32_e32 v65, v64, v159
	v_exp_f32_e32 v64, v80
	v_exp_f32_e32 v72, v65
	v_exp_f32_e32 v65, v81
	v_exp_f32_e32 v73, v66
	v_exp_f32_e32 v66, v82
	v_exp_f32_e32 v74, v67
	v_exp_f32_e32 v67, v83
	v_exp_f32_e32 v75, v68
	v_exp_f32_e32 v68, v84
	v_exp_f32_e32 v76, v69
	v_exp_f32_e32 v69, v85
	v_exp_f32_e32 v77, v70
	v_exp_f32_e32 v70, v86
	v_exp_f32_e32 v78, v71
	v_exp_f32_e32 v71, v87
	v_exp_f32_e32 v79, v79
	v_exp_f32_e32 v80, v88
	v_exp_f32_e32 v82, v221
	v_exp_f32_e32 v81, v89
	v_exp_f32_e32 v83, v220
	v_exp_f32_e32 v84, v90
	v_exp_f32_e32 v86, v219
	v_exp_f32_e32 v85, v91
	v_exp_f32_e32 v87, v218
	v_exp_f32_e32 v88, v92
	v_exp_f32_e32 v90, v217
	v_exp_f32_e32 v89, v93
	v_exp_f32_e32 v91, v177
	v_exp_f32_e32 v92, v94
	v_exp_f32_e32 v94, v167
	v_exp_f32_e32 v93, v95
	v_exp_f32_e32 v95, v163
	v_pk_add_f32 v[218:219], v[86:87], v[84:85]
	v_pk_add_f32 v[220:221], v[74:75], v[66:67]
	v_pk_add_f32 v[224:225], v[78:79], v[70:71]
	v_pk_add_f32 v[222:223], v[94:95], v[92:93]
	v_pk_add_f32 v[226:227], v[82:83], v[80:81]
	v_pk_add_f32 v[228:229], v[72:73], v[64:65]
	v_pk_add_f32 v[230:231], v[90:91], v[88:89]
	v_pk_add_f32 v[232:233], v[76:77], v[68:69]
	v_pk_add_f32 v[226:227], v[228:229], v[226:227]
	v_pk_add_f32 v[230:231], v[232:233], v[230:231]
	v_pk_add_f32 v[222:223], v[224:225], v[222:223]
	v_pk_add_f32 v[218:219], v[220:221], v[218:219]
	v_pk_add_f32 v[220:221], v[226:227], v[230:231]
	v_pk_add_f32 v[218:219], v[218:219], v[222:223]
	v_add_f32_e32 v167, v220, v221
	v_add_f32_e32 v177, v218, v219
	v_cndmask_b32_e64 v163, v196, 1.0, s[52:53]
	v_add_f32_e32 v167, v167, v177
	v_fmac_f32_e32 v167, v157, v163
	ds_read_b128 v[218:221], v252 offset:32768
	ds_read_b128 v[222:225], v252 offset:36864
	ds_read_b128 v[226:229], v253 offset:24576
	ds_read_b128 v[230:233], v253 offset:28672
	v_cvt_pk_bf16_f32 v64, v64, v65
	v_cvt_pk_bf16_f32 v65, v66, v67
	v_cvt_pk_bf16_f32 v66, v68, v69
	v_cvt_pk_bf16_f32 v67, v70, v71
	s_nop 0
	s_waitcnt lgkmcnt(5)
	v_mfma_f32_32x32x16_bf16 v[48:63], v[244:247], v[64:67], v[48:63]
	ds_read_b128 v[244:247], v253 offset:32768
	s_waitcnt lgkmcnt(5)
	v_mfma_f32_32x32x16_bf16 v[32:47], v[248:251], v[64:67], v[32:47]
	ds_read_b128 v[248:251], v253 offset:36864
	s_waitcnt lgkmcnt(5)
	v_mfma_f32_32x32x16_bf16 v[16:31], v[218:221], v[64:67], v[16:31]
	ds_read_b128 v[218:221], v254 offset:24576
	s_waitcnt lgkmcnt(5)
	v_mfma_f32_32x32x16_bf16 v[0:15], v[222:225], v[64:67], v[0:15]
	ds_read_b128 v[222:225], v254 offset:28672
	s_nop 0
	v_cvt_pk_bf16_f32 v64, v80, v81
	v_cvt_pk_bf16_f32 v65, v84, v85
	v_cvt_pk_bf16_f32 v66, v88, v89
	v_cvt_pk_bf16_f32 v67, v92, v93
	s_nop 0
	s_waitcnt lgkmcnt(5)
	v_mfma_f32_32x32x16_bf16 v[48:63], v[226:229], v[64:67], v[48:63]
	ds_read_b128 v[226:229], v254 offset:32768
	s_waitcnt lgkmcnt(5)
	v_mfma_f32_32x32x16_bf16 v[32:47], v[230:233], v[64:67], v[32:47]
	ds_read_b128 v[230:233], v254 offset:36864
	s_waitcnt lgkmcnt(5)
	v_mfma_f32_32x32x16_bf16 v[16:31], v[244:247], v[64:67], v[16:31]
	ds_read_b128 v[244:247], v255 offset:24576
	s_waitcnt lgkmcnt(5)
	v_mfma_f32_32x32x16_bf16 v[0:15], v[248:251], v[64:67], v[0:15]
	ds_read_b128 v[248:251], v255 offset:28672
	s_nop 0
	v_cvt_pk_bf16_f32 v64, v72, v73
	v_cvt_pk_bf16_f32 v65, v74, v75
	v_cvt_pk_bf16_f32 v66, v76, v77
	v_cvt_pk_bf16_f32 v67, v78, v79
	s_nop 0
	s_waitcnt lgkmcnt(5)
	v_mfma_f32_32x32x16_bf16 v[48:63], v[218:221], v[64:67], v[48:63]
	ds_read_b128 v[218:221], v255 offset:32768
	s_waitcnt lgkmcnt(5)
	v_mfma_f32_32x32x16_bf16 v[32:47], v[222:225], v[64:67], v[32:47]
	ds_read_b128 v[222:225], v255 offset:36864
	s_waitcnt lgkmcnt(5)
	v_mfma_f32_32x32x16_bf16 v[16:31], v[226:229], v[64:67], v[16:31]
	s_waitcnt lgkmcnt(4)
	v_mfma_f32_32x32x16_bf16 v[0:15], v[230:233], v[64:67], v[0:15]
	s_nop 0
	v_cvt_pk_bf16_f32 v64, v82, v83
	v_cvt_pk_bf16_f32 v65, v86, v87
	v_cvt_pk_bf16_f32 v66, v90, v91
	v_cvt_pk_bf16_f32 v67, v94, v95
	s_nop 0
	s_waitcnt lgkmcnt(3)
	v_mfma_f32_32x32x16_bf16 v[48:63], v[244:247], v[64:67], v[48:63]
	s_waitcnt lgkmcnt(2)
	v_mfma_f32_32x32x16_bf16 v[32:47], v[248:251], v[64:67], v[32:47]
	s_waitcnt lgkmcnt(1)
	v_mfma_f32_32x32x16_bf16 v[16:31], v[218:221], v[64:67], v[16:31]
	s_waitcnt lgkmcnt(0)
	v_mfma_f32_32x32x16_bf16 v[0:15], v[222:225], v[64:67], v[0:15]
	s_nop 0
	v_mov_b32_e32 v157, v167
	s_branch .LBB0_670

; #define LAS __attribute__((address_space(3)))
; __device__ __forceinline__ void attn_unit(LAS unsigned char* lds, const bf16_t* Q, const bf16_t* KN, const bf16_t* KPE, const bf16_t* VT, bf16_t* Y, float* ssq_b, int b, int h, int qg) {
;     ...
;         if (j <= cw) {
;             const LAS unsigned char* kb = lds + (j & 1) * KV_BYTES; const LAS unsigned char* vb = kb + KS_BYTES;
;             f32x16 s0, s1;
; #pragma unroll
;             for (int i = 0; i < 16; ++i) { s0[i] = 0.f; s1[i] = 0.f; }
;             __builtin_amdgcn_s_setprio(1);
;             {
;                 bf16x8 a0n = *(const LAS bf16x8*)(kb + kbase0), a1n = *(const LAS bf16x8*)(kb + (kbase0 + 32u * 384u));
; #pragma unroll
;                 for (int ks = 0; ks < 12; ++ks) {
;                     const bf16x8 a0 = a0n, a1 = a1n;
;                     if (ks + 1 < 12) { const unsigned off = (kbase0 ^ (unsigned)(((2 * (ks + 1)) & 7) << 4)) + (unsigned)(((2 * (ks + 1)) & 24) << 4);
;                         a0n = *(const LAS bf16x8*)(kb + off); a1n = *(const LAS bf16x8*)(kb + (off + 32u * 384u)); }
;                     s0 = __builtin_amdgcn_mfma_f32_32x32x16_bf16(a0, qf[ks], s0, 0, 0, 0);
;                     s1 = __builtin_amdgcn_mfma_f32_32x32x16_bf16(a1, qf[ks], s1, 0, 0, 0);
;                 }
;             }
;             __builtin_amdgcn_s_setprio(0);
;             if (j == 0) {
; #pragma unroll
;                 for (int i = 0; i < 16; ++i) { if (i >= 8) s0[i] = -INFINITY; s1[i] = -INFINITY; }
;             }
;             float mx = s0[0];
; #pragma unroll
;             for (int i = 1; i < 16; ++i) mx = fmaxf(mx, s0[i]);
; #pragma unroll
;             for (int i = 0; i < 16; ++i) mx = fmaxf(mx, s1[i]);
;             mx = fmaxf(mx, __shfl_xor(mx, 32));
;             const bool upd = __builtin_amdgcn_ballot_w64(mx - mrun > 8.0f) != 0ull;
;             const float mn = upd ? fmaxf(mrun, mx) : mrun; const float alpha = upd ? fexp2(mrun - mn) : 1.0f; mrun = mn;
;             s0 = s0 - mn; s1 = s1 - mn;
; #pragma unroll
;             for (int i = 0; i < 16; ++i) { s0[i] = fexp2(s0[i]); s1[i] = fexp2(s1[i]); }
;             const f32x16 t16 = s0 + s1;
;             typedef float f32x8_ __attribute__((ext_vector_type(8)));
;             const f32x8_ t8 = __builtin_shufflevector(t16, t16, 0, 1, 2, 3, 4, 5, 6, 7) + __builtin_shufflevector(t16, t16, 8, 9, 10, 11, 12, 13, 14, 15);
.LBB0_674:
	s_cmp_ge_u32 s52, s65
	s_cbranch_scc1 .LBB0_678
	s_nop 0
	v_add_u32_e32 v150, s8, v197
	v_add_u32_e32 v160, s8, v199
	v_add_u32_e32 v161, s8, v200
	v_add_u32_e32 v252, s8, v201
	ds_read_b128 v[218:221], v150
	ds_read_b128 v[222:225], v150 offset:12288
	ds_read_b128 v[226:229], v160
	ds_read_b128 v[230:233], v160 offset:12288
	ds_read_b128 v[244:247], v161
	ds_read_b128 v[248:251], v161 offset:12288
	s_waitcnt lgkmcnt(5)
	v_mfma_f32_32x32x16_bf16 v[80:95], v[218:221], v[140:143], 0
	ds_read_b128 v[218:221], v252
	s_waitcnt lgkmcnt(5)
	v_mfma_f32_32x32x16_bf16 v[64:79], v[222:225], v[140:143], 0
	ds_read_b128 v[222:225], v252 offset:12288
	s_waitcnt lgkmcnt(5)
	v_mfma_f32_32x32x16_bf16 v[80:95], v[226:229], v[136:139], v[80:95]
	ds_read_b128 v[226:229], v150 offset:128
	s_waitcnt lgkmcnt(5)
	v_mfma_f32_32x32x16_bf16 v[64:79], v[230:233], v[136:139], v[64:79]
	ds_read_b128 v[230:233], v150 offset:12416
	s_waitcnt lgkmcnt(5)
	v_mfma_f32_32x32x16_bf16 v[80:95], v[244:247], v[132:135], v[80:95]
	ds_read_b128 v[244:247], v160 offset:128
	s_waitcnt lgkmcnt(5)
	v_mfma_f32_32x32x16_bf16 v[64:79], v[248:251], v[132:135], v[64:79]
	ds_read_b128 v[248:251], v160 offset:12416
	s_waitcnt lgkmcnt(5)
	v_mfma_f32_32x32x16_bf16 v[80:95], v[218:221], v[128:131], v[80:95]
	ds_read_b128 v[218:221], v161 offset:128
	s_waitcnt lgkmcnt(5)
	v_mfma_f32_32x32x16_bf16 v[64:79], v[222:225], v[128:131], v[64:79]
	ds_read_b128 v[222:225], v161 offset:12416
	s_waitcnt lgkmcnt(5)
	v_mfma_f32_32x32x16_bf16 v[80:95], v[226:229], v[124:127], v[80:95]
	ds_read_b128 v[226:229], v252 offset:128
	s_waitcnt lgkmcnt(5)
	v_mfma_f32_32x32x16_bf16 v[64:79], v[230:233], v[124:127], v[64:79]
	ds_read_b128 v[230:233], v252 offset:12416
	s_waitcnt lgkmcnt(5)
	v_mfma_f32_32x32x16_bf16 v[80:95], v[244:247], v[120:123], v[80:95]
	ds_read_b128 v[244:247], v150 offset:256
	s_waitcnt lgkmcnt(5)
	v_mfma_f32_32x32x16_bf16 v[64:79], v[248:251], v[120:123], v[64:79]
	ds_read_b128 v[248:251], v150 offset:12544
	s_waitcnt lgkmcnt(5)
	v_mfma_f32_32x32x16_bf16 v[80:95], v[218:221], v[116:119], v[80:95]
	ds_read_b128 v[218:221], v160 offset:256
	s_waitcnt lgkmcnt(5)
	v_mfma_f32_32x32x16_bf16 v[64:79], v[222:225], v[116:119], v[64:79]
	ds_read_b128 v[222:225], v160 offset:12544
	s_waitcnt lgkmcnt(5)
	v_mfma_f32_32x32x16_bf16 v[80:95], v[226:229], v[112:115], v[80:95]
	ds_read_b128 v[226:229], v161 offset:256
	s_waitcnt lgkmcnt(5)
	v_mfma_f32_32x32x16_bf16 v[64:79], v[230:233], v[112:115], v[64:79]
	ds_read_b128 v[230:233], v161 offset:12544
	s_waitcnt lgkmcnt(5)
	v_mfma_f32_32x32x16_bf16 v[80:95], v[244:247], v[108:111], v[80:95]
	ds_read_b128 v[244:247], v252 offset:256
	s_waitcnt lgkmcnt(5)
	v_mfma_f32_32x32x16_bf16 v[64:79], v[248:251], v[108:111], v[64:79]
	ds_read_b128 v[248:251], v252 offset:12544
	s_waitcnt lgkmcnt(5)
	v_mfma_f32_32x32x16_bf16 v[80:95], v[218:221], v[104:107], v[80:95]
	s_waitcnt lgkmcnt(4)
	v_mfma_f32_32x32x16_bf16 v[64:79], v[222:225], v[104:107], v[64:79]
	s_waitcnt lgkmcnt(3)
	v_mfma_f32_32x32x16_bf16 v[80:95], v[226:229], v[100:103], v[80:95]
	s_waitcnt lgkmcnt(2)
	v_mfma_f32_32x32x16_bf16 v[64:79], v[230:233], v[100:103], v[64:79]
	s_waitcnt lgkmcnt(1)
	v_mfma_f32_32x32x16_bf16 v[80:95], v[244:247], v[96:99], v[80:95]
	s_waitcnt lgkmcnt(0)
	v_mfma_f32_32x32x16_bf16 v[64:79], v[248:251], v[96:99], v[64:79]
	s_nop 0
	s_nop 8
	v_max_f32_e32 v96, v81, v81
	v_max_f32_e32 v97, v80, v80
	v_max_f32_e32 v96, v97, v96
	v_max3_f32 v96, v96, v82, v83
	v_max3_f32 v96, v96, v84, v85
	v_max3_f32 v96, v96, v86, v87
	v_max3_f32 v96, v96, v88, v89
	v_max3_f32 v96, v96, v90, v91
	v_max3_f32 v96, v96, v92, v93
	v_max3_f32 v96, v96, v94, v95
	v_max3_f32 v96, v96, v64, v65
	v_max3_f32 v96, v96, v66, v67
	v_max3_f32 v96, v96, v68, v69
	v_max3_f32 v96, v96, v70, v71
	v_max3_f32 v96, v96, v72, v73
	v_max3_f32 v96, v96, v74, v75
	v_max3_f32 v96, v96, v76, v77
	v_max3_f32 v96, v96, v78, v79
	ds_bpermute_b32 v97, v205, v96
	s_waitcnt lgkmcnt(0)
	v_max_f32_e32 v97, v97, v97
	v_max_f32_e32 v96, v96, v97
	v_sub_f32_e32 v97, v96, v159
	v_cmp_lt_f32_e32 vcc, s38, v97
	s_cmp_eq_u64 vcc, 0
	v_max_f32_e32 v97, v159, v159
	s_cselect_b64 s[52:53], -1, 0
	v_max_f32_e32 v96, v97, v96
	v_cndmask_b32_e64 v97, v96, v159, s[52:53]
	v_sub_f32_e32 v96, v159, v97
	v_exp_f32_e32 v96, v96
	s_and_b64 vcc, exec, s[52:53]
	s_cbranch_vccnz .LBB0_677
	v_pk_mul_f32 v[62:63], v[62:63], v[96:97] op_sel_hi:[1,0]
	v_pk_mul_f32 v[60:61], v[60:61], v[96:97] op_sel_hi:[1,0]
	v_pk_mul_f32 v[58:59], v[58:59], v[96:97] op_sel_hi:[1,0]
	v_pk_mul_f32 v[56:57], v[56:57], v[96:97] op_sel_hi:[1,0]
	v_pk_mul_f32 v[54:55], v[54:55], v[96:97] op_sel_hi:[1,0]
	v_pk_mul_f32 v[52:53], v[52:53], v[96:97] op_sel_hi:[1,0]
	v_pk_mul_f32 v[50:51], v[50:51], v[96:97] op_sel_hi:[1,0]
	v_pk_mul_f32 v[48:49], v[48:49], v[96:97] op_sel_hi:[1,0]
	v_pk_mul_f32 v[46:47], v[46:47], v[96:97] op_sel_hi:[1,0]
	v_pk_mul_f32 v[44:45], v[44:45], v[96:97] op_sel_hi:[1,0]
	v_pk_mul_f32 v[42:43], v[42:43], v[96:97] op_sel_hi:[1,0]
	v_pk_mul_f32 v[40:41], v[40:41], v[96:97] op_sel_hi:[1,0]
	v_pk_mul_f32 v[38:39], v[38:39], v[96:97] op_sel_hi:[1,0]
	v_pk_mul_f32 v[36:37], v[36:37], v[96:97] op_sel_hi:[1,0]
	v_pk_mul_f32 v[34:35], v[34:35], v[96:97] op_sel_hi:[1,0]
	v_pk_mul_f32 v[32:33], v[32:33], v[96:97] op_sel_hi:[1,0]
	v_pk_mul_f32 v[30:31], v[30:31], v[96:97] op_sel_hi:[1,0]
	v_pk_mul_f32 v[28:29], v[28:29], v[96:97] op_sel_hi:[1,0]
	v_pk_mul_f32 v[26:27], v[26:27], v[96:97] op_sel_hi:[1,0]
	v_pk_mul_f32 v[24:25], v[24:25], v[96:97] op_sel_hi:[1,0]
	v_pk_mul_f32 v[22:23], v[22:23], v[96:97] op_sel_hi:[1,0]
	v_pk_mul_f32 v[20:21], v[20:21], v[96:97] op_sel_hi:[1,0]
	v_pk_mul_f32 v[18:19], v[18:19], v[96:97] op_sel_hi:[1,0]
	v_pk_mul_f32 v[16:17], v[16:17], v[96:97] op_sel_hi:[1,0]
	v_pk_mul_f32 v[14:15], v[14:15], v[96:97] op_sel_hi:[1,0]
	v_pk_mul_f32 v[12:13], v[12:13], v[96:97] op_sel_hi:[1,0]
	v_pk_mul_f32 v[10:11], v[10:11], v[96:97] op_sel_hi:[1,0]
	v_pk_mul_f32 v[8:9], v[8:9], v[96:97] op_sel_hi:[1,0]
	v_pk_mul_f32 v[6:7], v[6:7], v[96:97] op_sel_hi:[1,0]
	v_pk_mul_f32 v[4:5], v[4:5], v[96:97] op_sel_hi:[1,0]
	v_pk_mul_f32 v[2:3], v[2:3], v[96:97] op_sel_hi:[1,0]
	v_pk_mul_f32 v[0:1], v[0:1], v[96:97] op_sel_hi:[1,0]
; #define LAS __attribute__((address_space(3)))
; __device__ __forceinline__ void attn_unit(LAS unsigned char* lds, const bf16_t* Q, const bf16_t* KN, const bf16_t* KPE, const bf16_t* VT, bf16_t* Y, float* ssq_b, int b, int h, int qg) {
;     ...
;             const float mn = upd ? fmaxf(mrun, mx) : mrun; const float alpha = upd ? fexp2(mrun - mn) : 1.0f; mrun = mn;
;             s0 = s0 - mn; s1 = s1 - mn;
; #pragma unroll
;             for (int i = 0; i < 16; ++i) { s0[i] = fexp2(s0[i]); s1[i] = fexp2(s1[i]); }
;             const f32x16 t16 = s0 + s1;
;             typedef float f32x8_ __attribute__((ext_vector_type(8)));
;             const f32x8_ t8 = __builtin_shufflevector(t16, t16, 0, 1, 2, 3, 4, 5, 6, 7) + __builtin_shufflevector(t16, t16, 8, 9, 10, 11, 12, 13, 14, 15);
;             const f32x4 t4 = __builtin_shufflevector(t8, t8, 0, 1, 2, 3) + __builtin_shufflevector(t8, t8, 4, 5, 6, 7);
;             const float ps = (t4[0] + t4[1]) + (t4[2] + t4[3]);
;             lsum = lsum * alpha + ps;
;             if (upd) {
; #pragma unroll
;                 for (int d = 0; d < 4; ++d)
; #pragma unroll
;                     for (int i = 0; i < 16; ++i) o[d][i] *= alpha;
;             }
; #pragma unroll
;             for (int kb2 = 0; kb2 < 2; ++kb2)
; #pragma unroll
;                 for (int a = 0; a < 2; ++a) {
;                     u32x4 pw;
;                     if (kb2 == 0) { pw.x = cvt_pk(s0[8 * a + 0], s0[8 * a + 1]); pw.y = cvt_pk(s0[8 * a + 2], s0[8 * a + 3]); pw.z = cvt_pk(s0[8 * a + 4], s0[8 * a + 5]); pw.w = cvt_pk(s0[8 * a + 6], s0[8 * a + 7]); }
;                     else { pw.x = cvt_pk(s1[8 * a + 0], s1[8 * a + 1]); pw.y = cvt_pk(s1[8 * a + 2], s1[8 * a + 3]); pw.z = cvt_pk(s1[8 * a + 4], s1[8 * a + 5]); pw.w = cvt_pk(s1[8 * a + 6], s1[8 * a + 7]); }
;                     const bf16x8 pf = __builtin_bit_cast(bf16x8, pw);
;                     const unsigned vro = vbase0 ^ (unsigned)((4 * kb2 + 2 * a) << 4);
;                     __builtin_amdgcn_s_setprio(1);
; #pragma unroll
;                     for (int db = 0; db < 4; ++db) {
;                         const bf16x8 vf = *(const LAS bf16x8*)(vb + (vro + (unsigned)(db * 4096)));
;                         o[db] = __builtin_amdgcn_mfma_f32_32x32x16_bf16(vf, pf, o[db], 0, 0, 0);
;                     }
;                     __builtin_amdgcn_s_setprio(0);
;                 }
.LBB0_677:
	v_sub_f32_e32 v95, v95, v97
	v_sub_f32_e32 v94, v94, v97
	v_sub_f32_e32 v93, v93, v97
	v_sub_f32_e32 v92, v92, v97
	v_sub_f32_e32 v91, v91, v97
	v_sub_f32_e32 v90, v90, v97
	v_sub_f32_e32 v89, v89, v97
	v_sub_f32_e32 v88, v88, v97
	v_sub_f32_e32 v87, v87, v97
	v_sub_f32_e32 v86, v86, v97
	v_sub_f32_e32 v85, v85, v97
	v_sub_f32_e32 v84, v84, v97
	v_sub_f32_e32 v83, v83, v97
	v_sub_f32_e32 v82, v82, v97
	v_sub_f32_e32 v81, v81, v97
	v_sub_f32_e32 v80, v80, v97
	v_sub_f32_e32 v98, v79, v97
	v_sub_f32_e32 v99, v78, v97
	v_sub_f32_e32 v100, v77, v97
	v_sub_f32_e32 v101, v76, v97
	v_sub_f32_e32 v102, v75, v97
	v_sub_f32_e32 v103, v74, v97
	v_sub_f32_e32 v104, v73, v97
	v_sub_f32_e32 v105, v72, v97
	v_sub_f32_e32 v79, v71, v97
	v_sub_f32_e32 v71, v70, v97
	v_sub_f32_e32 v70, v69, v97
	v_sub_f32_e32 v69, v68, v97
	v_sub_f32_e32 v68, v67, v97
	v_sub_f32_e32 v67, v66, v97
	v_sub_f32_e32 v66, v65, v97
	v_sub_f32_e32 v65, v64, v97
	v_exp_f32_e32 v64, v80
	v_exp_f32_e32 v72, v65
	v_exp_f32_e32 v65, v81
	v_exp_f32_e32 v73, v66
	v_exp_f32_e32 v66, v82
	v_exp_f32_e32 v74, v67
	v_exp_f32_e32 v67, v83
	v_exp_f32_e32 v75, v68
	v_exp_f32_e32 v68, v84
	v_exp_f32_e32 v76, v69
	v_exp_f32_e32 v69, v85
	v_exp_f32_e32 v77, v70
	v_exp_f32_e32 v70, v86
	v_exp_f32_e32 v78, v71
	v_exp_f32_e32 v71, v87
	v_exp_f32_e32 v79, v79
	v_exp_f32_e32 v80, v88
	v_exp_f32_e32 v82, v105
	v_exp_f32_e32 v81, v89
	v_exp_f32_e32 v83, v104
	v_exp_f32_e32 v84, v90
	v_exp_f32_e32 v86, v103
	v_exp_f32_e32 v85, v91
	v_exp_f32_e32 v87, v102
	v_exp_f32_e32 v88, v92
	v_exp_f32_e32 v90, v101
	v_exp_f32_e32 v89, v93
	v_exp_f32_e32 v91, v100
	v_exp_f32_e32 v92, v94
	v_exp_f32_e32 v94, v99
	v_exp_f32_e32 v93, v95
	v_exp_f32_e32 v95, v98
	v_cndmask_b32_e64 v112, v96, 1.0, s[52:53]
	v_pk_add_f32 v[96:97], v[86:87], v[84:85]
	v_pk_add_f32 v[98:99], v[74:75], v[66:67]
	v_pk_add_f32 v[100:101], v[94:95], v[92:93]
	v_pk_add_f32 v[102:103], v[78:79], v[70:71]
	v_pk_add_f32 v[104:105], v[82:83], v[80:81]
	v_pk_add_f32 v[106:107], v[72:73], v[64:65]
	v_pk_add_f32 v[108:109], v[90:91], v[88:89]
	v_pk_add_f32 v[110:111], v[76:77], v[68:69]
	v_pk_add_f32 v[104:105], v[106:107], v[104:105]
	v_pk_add_f32 v[108:109], v[110:111], v[108:109]
	v_pk_add_f32 v[100:101], v[102:103], v[100:101]
	v_pk_add_f32 v[96:97], v[98:99], v[96:97]
	v_pk_add_f32 v[98:99], v[104:105], v[108:109]
	v_pk_add_f32 v[96:97], v[96:97], v[100:101]
	v_add_f32_e32 v98, v98, v99
	v_add_f32_e32 v96, v96, v97
	v_add_f32_e32 v96, v98, v96
	v_fmac_f32_e32 v96, v157, v112
	v_add_u32_e32 v252, s8, v198
	v_add_u32_e32 v253, s8, v202
	v_add_u32_e32 v254, s8, v203
	v_add_u32_e32 v255, s8, v204
	ds_read_b128 v[218:221], v252 offset:24576
	ds_read_b128 v[222:225], v252 offset:28672
	ds_read_b128 v[226:229], v252 offset:32768
	ds_read_b128 v[230:233], v252 offset:36864
	ds_read_b128 v[244:247], v253 offset:24576
	ds_read_b128 v[248:251], v253 offset:28672
	v_cvt_pk_bf16_f32 v64, v64, v65
	v_cvt_pk_bf16_f32 v65, v66, v67
	v_cvt_pk_bf16_f32 v66, v68, v69
	v_cvt_pk_bf16_f32 v67, v70, v71
	s_nop 0
	s_waitcnt lgkmcnt(5)
	v_mfma_f32_32x32x16_bf16 v[48:63], v[218:221], v[64:67], v[48:63]
	ds_read_b128 v[218:221], v253 offset:32768
	s_waitcnt lgkmcnt(5)
	v_mfma_f32_32x32x16_bf16 v[32:47], v[222:225], v[64:67], v[32:47]
	ds_read_b128 v[222:225], v253 offset:36864
	s_waitcnt lgkmcnt(5)
	v_mfma_f32_32x32x16_bf16 v[16:31], v[226:229], v[64:67], v[16:31]
	ds_read_b128 v[226:229], v254 offset:24576
	s_waitcnt lgkmcnt(5)
	v_mfma_f32_32x32x16_bf16 v[0:15], v[230:233], v[64:67], v[0:15]
	ds_read_b128 v[230:233], v254 offset:28672
	s_nop 0
	v_cvt_pk_bf16_f32 v64, v80, v81
	v_cvt_pk_bf16_f32 v65, v84, v85
	v_cvt_pk_bf16_f32 v66, v88, v89
	v_cvt_pk_bf16_f32 v67, v92, v93
	s_nop 0
	s_waitcnt lgkmcnt(5)
	v_mfma_f32_32x32x16_bf16 v[48:63], v[244:247], v[64:67], v[48:63]
	ds_read_b128 v[244:247], v254 offset:32768
	s_waitcnt lgkmcnt(5)
	v_mfma_f32_32x32x16_bf16 v[32:47], v[248:251], v[64:67], v[32:47]
	ds_read_b128 v[248:251], v254 offset:36864
	s_waitcnt lgkmcnt(5)
	v_mfma_f32_32x32x16_bf16 v[16:31], v[218:221], v[64:67], v[16:31]
	ds_read_b128 v[218:221], v255 offset:24576
	s_waitcnt lgkmcnt(5)
	v_mfma_f32_32x32x16_bf16 v[0:15], v[222:225], v[64:67], v[0:15]
	ds_read_b128 v[222:225], v255 offset:28672
	s_nop 0
	v_cvt_pk_bf16_f32 v64, v72, v73
	v_cvt_pk_bf16_f32 v65, v74, v75
	v_cvt_pk_bf16_f32 v66, v76, v77
	v_cvt_pk_bf16_f32 v67, v78, v79
	s_nop 0
	s_waitcnt lgkmcnt(5)
	v_mfma_f32_32x32x16_bf16 v[48:63], v[226:229], v[64:67], v[48:63]
	ds_read_b128 v[226:229], v255 offset:32768
	s_waitcnt lgkmcnt(5)
	v_mfma_f32_32x32x16_bf16 v[32:47], v[230:233], v[64:67], v[32:47]
	ds_read_b128 v[230:233], v255 offset:36864
	s_waitcnt lgkmcnt(5)
	v_mfma_f32_32x32x16_bf16 v[16:31], v[244:247], v[64:67], v[16:31]
	s_waitcnt lgkmcnt(4)
	v_mfma_f32_32x32x16_bf16 v[0:15], v[248:251], v[64:67], v[0:15]
	s_nop 0
	v_cvt_pk_bf16_f32 v64, v82, v83
	v_cvt_pk_bf16_f32 v65, v86, v87
	v_cvt_pk_bf16_f32 v66, v90, v91
	v_cvt_pk_bf16_f32 v67, v94, v95
	s_nop 0
	s_waitcnt lgkmcnt(3)
	v_mfma_f32_32x32x16_bf16 v[48:63], v[218:221], v[64:67], v[48:63]
	s_waitcnt lgkmcnt(2)
	v_mfma_f32_32x32x16_bf16 v[32:47], v[222:225], v[64:67], v[32:47]
	s_waitcnt lgkmcnt(1)
	v_mfma_f32_32x32x16_bf16 v[16:31], v[226:229], v[64:67], v[16:31]
	s_waitcnt lgkmcnt(0)
	v_mfma_f32_32x32x16_bf16 v[0:15], v[230:233], v[64:67], v[0:15]
	s_nop 0
	v_mov_b32_e32 v157, v96

; #define LAS __attribute__((address_space(3)))
; __device__ __forceinline__ int pi32(int r) { return (r & 0x13) | ((r & 4) << 1) | ((r & 8) >> 1); }
; __device__ __forceinline__ void attn_unit(LAS unsigned char* lds, const bf16_t* Q, const bf16_t* KN, const bf16_t* KPE, const bf16_t* VT, bf16_t* Y, float* ssq_b, int b, int h, int qg) {
;     const int tid = threadIdx.x, wid = __builtin_amdgcn_readfirstlane(tid >> 6), lane = tid & 63, q = lane & 31, hh = lane >> 5;
;     const int t0 = 16 + 256 * qg, c0 = 1 + 4 * qg, cw = c0 + (wid >> 1), ntiles = c0 + 4;
;     bf16x8 qf[12];
;     {
;         const bf16_t* qp = Q + (size_t)(b * 2048 + (t0 - 16) + 32 * wid + q) * 1536 + h * 192 + 8 * hh;
; #pragma unroll
;         for (int ks = 0; ks < 12; ++ks) qf[ks] = *(const bf16x8*)(qp + 16 * ks);
;     }
;     f32x16 o[4];
; #pragma unroll
;     for (int d = 0; d < 4; ++d)
; #pragma unroll
;         for (int i = 0; i < 16; ++i) o[d][i] = 0.f;
;     float mrun = -INFINITY, lsum = 0.f;
;     const char* ksrc[3]; unsigned kstr[3]; const char* vsrc[2];
; #pragma unroll
;     for (int i = 0; i < 3; ++i) {
;         const int s = 64 * (wid * 3 + i) + lane; const int key = s / 24, pos = s - key * 24; const int pc = pos ^ ((key >> 1) & 7);
;         const size_t row = (size_t)b * 2048 + key;
;         if (pc < 16) { ksrc[i] = (const char*)(KN + row * 1024 + h * 128 + pc * 8); kstr[i] = 2048u; }
;         else { ksrc[i] = (const char*)(KPE + row * 64 + (pc - 16) * 8); kstr[i] = 128u; }
;     }
; #pragma unroll
;     for (int i = 0; i < 2; ++i) {
;         const int s = 64 * (wid * 2 + i) + lane; const int d = s >> 3, pos = s & 7; const int pc = pos ^ ((d >> 1) & 7);
;         vsrc[i] = (const char*)(VT + ((size_t)((b * 8 + h) * 128 + d)) * 2048 + pc * 8);
;     }
;     ...
;     const int key0 = pi32(q);
;     const unsigned kbase0 = (unsigned)(key0 * 384) + (unsigned)(((hh ^ ((key0 >> 1) & 7))) << 4);
;     const unsigned vbase0 = (unsigned)(q * 128) + (unsigned)((hh ^ ((q >> 1) & 7)) << 4);
;     AT_DMA(0); __syncthreads();
.LBB0_680:
	s_or_b64 exec, exec, s[8:9]
	v_readfirstlane_b32 s52, v170
	s_lshr_b32 s53, s52, 6
	s_lshl_b32 s13, s45, 8
	s_lshl_b32 s28, s53, 5
	v_or_b32_e32 v0, s13, v211
	v_add_u32_e32 v2, s28, v0
	s_waitcnt lgkmcnt(0)
	v_mov_b64_e32 v[0:1], s[60:61]
	v_mad_i64_i32 v[0:1], s[8:9], v2, s31, v[0:1]
	v_lshl_add_u64 v[0:1], v[0:1], 0, s[16:17]
	v_mov_b32_e32 v157, v151
	v_lshl_add_u64 v[0:1], v[0:1], 0, v[156:157]
	global_load_dwordx4 v[140:143], v[0:1], off
	global_load_dwordx4 v[136:139], v[0:1], off offset:32
	global_load_dwordx4 v[132:135], v[0:1], off offset:64
	global_load_dwordx4 v[128:131], v[0:1], off offset:96
	global_load_dwordx4 v[124:127], v[0:1], off offset:128
	global_load_dwordx4 v[120:123], v[0:1], off offset:160
	global_load_dwordx4 v[116:119], v[0:1], off offset:192
	global_load_dwordx4 v[112:115], v[0:1], off offset:224
	global_load_dwordx4 v[108:111], v[0:1], off offset:256
	global_load_dwordx4 v[104:107], v[0:1], off offset:288
	global_load_dwordx4 v[100:103], v[0:1], off offset:320
	global_load_dwordx4 v[96:99], v[0:1], off offset:352
	s_mul_i32 s8, s53, 0xc0
	v_or_b32_e32 v0, s8, v144
	v_mul_hi_u32 v2, v0, s34
	v_lshrrev_b32_e32 v150, 4, v2
	v_mad_u64_u32 v[0:1], s[8:9], v150, s35, v[0:1]
	v_lshrrev_b32_e32 v1, 5, v2
	v_bitop3_b32 v0, v0, v1, 7 bitop3:0x78
	v_lshl_add_u64 v[2:3], s[24:25], 0, v[150:151]
	v_cmp_lt_i32_e32 vcc, 15, v0
	v_lshlrev_b32_e32 v0, 3, v0
	s_and_saveexec_b64 s[8:9], vcc
	s_xor_b64 s[8:9], exec, s[8:9]
	v_lshlrev_b64 v[2:3], 7, v[2:3]
	v_lshl_add_u64 v[2:3], s[14:15], 0, v[2:3]
	v_add_u32_e32 v150, 0xffffff80, v0
	v_lshl_add_u64 v[160:161], v[150:151], 1, v[2:3]
	s_or_saveexec_b64 s[8:9], s[8:9]
	v_mov_b64_e32 v[162:163], 0x80
	s_xor_b64 exec, exec, s[8:9]
	v_lshlrev_b64 v[2:3], 11, v[2:3]
	v_lshl_add_u64 v[2:3], s[6:7], 0, v[2:3]
	v_ashrrev_i32_e32 v1, 31, v0
	v_lshl_add_u64 v[160:161], v[0:1], 1, v[2:3]
	v_mov_b64_e32 v[162:163], 0x800
	s_or_b64 exec, exec, s[8:9]
	s_mul_i32 s57, s53, 3
	s_add_i32 s16, s57, 1
	v_lshl_or_b32 v0, s16, 6, v144
	v_mul_hi_u32 v2, v0, s36
	v_lshrrev_b32_e32 v150, 2, v2
	v_mad_u64_u32 v[0:1], s[8:9], v150, s35, v[0:1]
	v_lshrrev_b32_e32 v1, 3, v2
	v_bitop3_b32 v0, v0, v1, 7 bitop3:0x78
	v_lshl_add_u64 v[2:3], s[24:25], 0, v[150:151]
	v_cmp_lt_i32_e32 vcc, 15, v0
	v_lshlrev_b32_e32 v0, 3, v0
	s_and_saveexec_b64 s[8:9], vcc
	s_xor_b64 s[8:9], exec, s[8:9]
	v_lshlrev_b64 v[2:3], 7, v[2:3]
	v_lshl_add_u64 v[2:3], s[14:15], 0, v[2:3]
	v_add_u32_e32 v150, 0xffffff80, v0
	v_lshl_add_u64 v[164:165], v[150:151], 1, v[2:3]
	s_or_saveexec_b64 s[8:9], s[8:9]
	v_mov_b64_e32 v[166:167], 0x80
	s_xor_b64 exec, exec, s[8:9]
	v_lshlrev_b64 v[2:3], 11, v[2:3]
	v_lshl_add_u64 v[2:3], s[6:7], 0, v[2:3]
	v_ashrrev_i32_e32 v1, 31, v0
	v_lshl_add_u64 v[164:165], v[0:1], 1, v[2:3]
	v_mov_b64_e32 v[166:167], 0x800
	s_or_b64 exec, exec, s[8:9]
	s_add_i32 s57, s57, 2
	v_lshl_or_b32 v0, s57, 6, v144
	v_mul_hi_u32 v2, v0, s36
	v_lshrrev_b32_e32 v150, 2, v2
	v_mad_u64_u32 v[0:1], s[8:9], v150, s35, v[0:1]
	v_lshrrev_b32_e32 v1, 3, v2
	v_bitop3_b32 v0, v0, v1, 7 bitop3:0x78
	v_lshl_add_u64 v[2:3], s[24:25], 0, v[150:151]
	v_cmp_lt_i32_e32 vcc, 15, v0
	v_lshlrev_b32_e32 v0, 3, v0
	s_and_saveexec_b64 s[8:9], vcc
	s_xor_b64 s[8:9], exec, s[8:9]
	v_lshlrev_b64 v[2:3], 7, v[2:3]
	v_lshl_add_u64 v[2:3], s[14:15], 0, v[2:3]
	v_add_u32_e32 v150, 0xffffff80, v0
	v_lshl_add_u64 v[168:169], v[150:151], 1, v[2:3]
	s_or_saveexec_b64 s[8:9], s[8:9]
	v_mov_b64_e32 v[176:177], 0x80
	s_xor_b64 exec, exec, s[8:9]
	v_lshlrev_b64 v[2:3], 11, v[2:3]
	v_lshl_add_u64 v[2:3], s[6:7], 0, v[2:3]
	v_ashrrev_i32_e32 v1, 31, v0
	v_lshl_add_u64 v[168:169], v[0:1], 1, v[2:3]
	v_mov_b64_e32 v[176:177], 0x800
	s_or_b64 exec, exec, s[8:9]
	v_lshl_or_b32 v2, s53, 7, v144
	v_ashrrev_i32_e32 v73, 3, v2
	v_add_u32_e32 v0, s54, v73
	v_ashrrev_i32_e32 v1, 31, v0
	v_lshlrev_b64 v[0:1], 12, v[0:1]
	v_lshl_add_u64 v[178:179], v[152:153], 0, v[0:1]
	v_or_b32_e32 v0, 64, v2
	v_ashrrev_i32_e32 v74, 3, v0
	v_lshrrev_b32_e32 v75, 4, v0
	v_add_u32_e32 v0, s54, v74
	v_xor_b32_e32 v2, v75, v170
	v_ashrrev_i32_e32 v1, 31, v0
	v_lshlrev_b64 v[0:1], 12, v[0:1]
	v_lshlrev_b32_e32 v2, 4, v2
	v_lshl_add_u64 v[0:1], s[42:43], 0, v[0:1]
	v_and_b32_e32 v150, 0x70, v2
	v_lshl_add_u64 v[180:181], v[0:1], 0, v[150:151]
	v_mad_u64_u32 v[0:1], s[6:7], v162, s55, v[160:161]
	s_mul_i32 s7, s53, 0xc00
	s_add_i32 s6, s7, 0
	s_mov_b32 m0, s6
	s_nop 0
	global_load_lds_dwordx4 v[0:1], off
	v_mad_u64_u32 v[0:1], s[8:9], v166, s55, v[164:165]
	s_lshl_b32 s8, s16, 10
	s_add_i32 s16, s8, 0
	s_mov_b32 m0, s16
	s_lshl_b32 s9, s57, 10
	global_load_lds_dwordx4 v[0:1], off
	v_mad_u64_u32 v[0:1], s[54:55], v176, s55, v[168:169]
	s_add_i32 s50, s9, 0
	s_lshl_b32 s54, s53, 11
	s_mov_b32 m0, s50
	s_add_i32 s51, s54, 0
	global_load_lds_dwordx4 v[0:1], off
	s_add_i32 m0, s51, 0x6000
	v_lshl_add_u64 v[0:1], v[178:179], 0, s[10:11]
	global_load_lds_dwordx4 v[0:1], off
	v_lshl_add_u64 v[0:1], v[180:181], 0, s[10:11]
	s_add_i32 m0, s51, 0x6400
	s_lshl_b32 s11, s45, 2
	global_load_lds_dwordx4 v[0:1], off
	s_add_i32 m0, s6, 0xa000
	s_waitcnt vmcnt(0) lgkmcnt(0)
	s_barrier
; __device__ __forceinline__ void attn_unit(LAS unsigned char* lds, const bf16_t* Q, const bf16_t* KN, const bf16_t* KPE, const bf16_t* VT, bf16_t* Y, float* ssq_b, int b, int h, int qg) {
;     ...
;         if (j + 1 < ntiles) AT_DMA(j + 1);
;         if (j <= cw) {
;             const LAS unsigned char* kb = lds + (j & 1) * KV_BYTES; const LAS unsigned char* vb = kb + KS_BYTES;
;             f32x16 s0, s1;
; #pragma unroll
;             for (int i = 0; i < 16; ++i) { s0[i] = 0.f; s1[i] = 0.f; }
;             __builtin_amdgcn_s_setprio(1);
;             {
;                 bf16x8 a0n = *(const LAS bf16x8*)(kb + kbase0), a1n = *(const LAS bf16x8*)(kb + (kbase0 + 32u * 384u));
; #pragma unroll
;                 for (int ks = 0; ks < 12; ++ks) {
;                     const bf16x8 a0 = a0n, a1 = a1n;
;                     if (ks + 1 < 12) { const unsigned off = (kbase0 ^ (unsigned)(((2 * (ks + 1)) & 7) << 4)) + (unsigned)(((2 * (ks + 1)) & 24) << 4);
;                         a0n = *(const LAS bf16x8*)(kb + off); a1n = *(const LAS bf16x8*)(kb + (off + 32u * 384u)); }
;                     s0 = __builtin_amdgcn_mfma_f32_32x32x16_bf16(a0, qf[ks], s0, 0, 0, 0);
;                     s1 = __builtin_amdgcn_mfma_f32_32x32x16_bf16(a1, qf[ks], s1, 0, 0, 0);
;                 }
;             }
;             __builtin_amdgcn_s_setprio(0);
;             if (j == 0) {
; #pragma unroll
;                 for (int i = 0; i < 16; ++i) { if (i >= 8) s0[i] = -INFINITY; s1[i] = -INFINITY; }
;             }
;             float mx = s0[0];
; #pragma unroll
;             for (int i = 1; i < 16; ++i) mx = fmaxf(mx, s0[i]);
; #pragma unroll
;             for (int i = 0; i < 16; ++i) mx = fmaxf(mx, s1[i]);
;             mx = fmaxf(mx, __shfl_xor(mx, 32));
;             const bool upd = __builtin_amdgcn_ballot_w64(mx - mrun > 8.0f) != 0ull;
;             const float mn = upd ? fmaxf(mrun, mx) : mrun; const float alpha = upd ? fexp2(mrun - mn) : 1.0f; mrun = mn;
;             s0 = s0 - mn; s1 = s1 - mn;
; #pragma unroll
;             for (int i = 0; i < 16; ++i) { s0[i] = fexp2(s0[i]); s1[i] = fexp2(s1[i]); }
;             const f32x16 t16 = s0 + s1;
;             typedef float f32x8_ __attribute__((ext_vector_type(8)));
;             const f32x8_ t8 = __builtin_shufflevector(t16, t16, 0, 1, 2, 3, 4, 5, 6, 7) + __builtin_shufflevector(t16, t16, 8, 9, 10, 11, 12, 13, 14, 15);
	global_load_lds_dwordx4 v[160:161], off
	s_add_i32 m0, s16, 0xa000
	s_lshr_b32 s6, s52, 7
	global_load_lds_dwordx4 v[164:165], off
	s_add_i32 m0, s50, 0xa000
	s_add_i32 s10, s6, s11
	global_load_lds_dwordx4 v[168:169], off
	s_add_i32 m0, s51, 0x10000
	s_and_b32 s6, s56, 3
	global_load_lds_dwordx4 v[178:179], off
	s_add_i32 m0, s51, 0x10400
	s_add_i32 s10, s10, 1
	global_load_lds_dwordx4 v[180:181], off
	s_lshl_b32 s16, s6, 2
	s_nop 0
	ds_read_b128 v[0:3], v209
	ds_read_b128 v[16:19], v210
	ds_read_b128 v[20:23], v208
	ds_read_b128 v[24:27], v207
	ds_read_b128 v[28:31], v209 offset:128
	ds_read_b128 v[32:35], v210 offset:128
	ds_read_b128 v[36:39], v208 offset:128
	ds_read_b128 v[40:43], v207 offset:128
	ds_read_b128 v[44:47], v209 offset:256
	ds_read_b128 v[48:51], v210 offset:256
	ds_read_b128 v[52:55], v208 offset:256
	ds_read_b128 v[56:59], v207 offset:256
	s_waitcnt lgkmcnt(11)
	v_mfma_f32_32x32x16_bf16 v[0:15], v[0:3], v[140:143], 0
	s_waitcnt lgkmcnt(10)
	v_mfma_f32_32x32x16_bf16 v[0:15], v[16:19], v[136:139], v[0:15]
	s_waitcnt lgkmcnt(9)
	v_mfma_f32_32x32x16_bf16 v[0:15], v[20:23], v[132:135], v[0:15]
	s_waitcnt lgkmcnt(8)
	v_mfma_f32_32x32x16_bf16 v[0:15], v[24:27], v[128:131], v[0:15]
	s_waitcnt lgkmcnt(7)
	v_mfma_f32_32x32x16_bf16 v[0:15], v[28:31], v[124:127], v[0:15]
	s_waitcnt lgkmcnt(6)
	v_mfma_f32_32x32x16_bf16 v[0:15], v[32:35], v[120:123], v[0:15]
	s_waitcnt lgkmcnt(5)
	v_mfma_f32_32x32x16_bf16 v[0:15], v[36:39], v[116:119], v[0:15]
	s_waitcnt lgkmcnt(4)
	v_mfma_f32_32x32x16_bf16 v[0:15], v[40:43], v[112:115], v[0:15]
	s_waitcnt lgkmcnt(3)
	v_mfma_f32_32x32x16_bf16 v[0:15], v[44:47], v[108:111], v[0:15]
	s_waitcnt lgkmcnt(2)
	v_mfma_f32_32x32x16_bf16 v[0:15], v[48:51], v[104:107], v[0:15]
	s_waitcnt lgkmcnt(1)
	v_mfma_f32_32x32x16_bf16 v[0:15], v[52:55], v[100:103], v[0:15]
	s_waitcnt lgkmcnt(0)
	v_mfma_f32_32x32x16_bf16 v[0:15], v[56:59], v[96:99], v[0:15]
	s_nop 0
	s_nop 10
	v_max3_f32 v8, v0, v1, v2
	v_max3_f32 v8, v8, v3, v4
	v_max3_f32 v8, v8, v5, v6
	v_max3_f32 v8, v8, v7, s37
	ds_bpermute_b32 v9, v205, v8
	s_waitcnt lgkmcnt(0)
	v_max_f32_e32 v9, v9, v9
	v_max_f32_e32 v8, v8, v9
	v_add_f32_e32 v9, 0x7f800000, v8
	v_cmp_lt_f32_e32 vcc, s38, v9
	s_cmp_eq_u64 vcc, 0
	v_max_f32_e32 v8, 0xff800000, v8
	s_cselect_b64 vcc, -1, 0
	v_cndmask_b32_e32 v163, v8, v206, vcc
	v_sub_f32_e32 v8, 0xff800000, v163
	v_sub_f32_e32 v7, v7, v163
	v_sub_f32_e32 v6, v6, v163
	v_sub_f32_e32 v5, v5, v163
	v_sub_f32_e32 v4, v4, v163
	v_sub_f32_e32 v3, v3, v163
	v_sub_f32_e32 v2, v2, v163
	v_sub_f32_e32 v1, v1, v163
	v_sub_f32_e32 v0, v0, v163
	v_exp_f32_e32 v72, v8
	v_exp_f32_e32 v16, v0
	v_exp_f32_e32 v17, v1
	v_exp_f32_e32 v18, v2
	v_exp_f32_e32 v19, v3
	v_exp_f32_e32 v20, v6
	v_exp_f32_e32 v21, v7
	v_exp_f32_e32 v22, v4
	v_exp_f32_e32 v23, v5
	v_pk_add_f32 v[0:1], v[72:73], v[18:19] op_sel_hi:[0,1]
	v_pk_add_f32 v[2:3], v[72:73], v[20:21] op_sel_hi:[0,1]
	v_pk_add_f32 v[4:5], v[72:73], v[16:17] op_sel_hi:[0,1]
	v_pk_add_f32 v[6:7], v[72:73], v[22:23] op_sel_hi:[0,1]
	v_pk_fma_f32 v[6:7], v[72:73], 2.0, v[6:7] op_sel_hi:[0,0,1]
	v_pk_fma_f32 v[4:5], v[72:73], 2.0, v[4:5] op_sel_hi:[0,0,1]
	v_pk_fma_f32 v[2:3], v[72:73], 2.0, v[2:3] op_sel_hi:[0,0,1]
	v_pk_fma_f32 v[0:1], v[72:73], 2.0, v[0:1] op_sel_hi:[0,0,1]
	v_pk_add_f32 v[0:1], v[0:1], v[2:3]
	v_pk_add_f32 v[2:3], v[4:5], v[6:7]
	v_cvt_pk_bf16_f32 v64, v16, v17
	v_cvt_pk_bf16_f32 v65, v18, v19
	v_cvt_pk_bf16_f32 v66, v22, v23
	v_cvt_pk_bf16_f32 v67, v20, v21
	s_nop 0
	v_pk_mov_b32 v[4:5], v[2:3], v[0:1] op_sel:[1,0]
	v_mov_b32_e32 v3, v1
	v_pk_add_f32 v[0:1], v[4:5], v[2:3]
	s_nop 0
	v_add_f32_e32 v1, v0, v1
	v_mul_f32_e32 v0, 0, v72
	v_cndmask_b32_e64 v0, v0, 0, vcc
	v_add_f32_e32 v157, v0, v1
	v_mov_b32_e32 v1, v0
	v_mov_b32_e32 v2, v0
	v_mov_b32_e32 v3, v0
	v_mov_b32_e32 v4, v0
	v_mov_b32_e32 v5, v0
	v_mov_b32_e32 v6, v0
	v_mov_b32_e32 v7, v0
	v_mov_b32_e32 v8, v0
	v_mov_b32_e32 v9, v0
	v_mov_b32_e32 v10, v0
	v_mov_b32_e32 v11, v0
	v_mov_b32_e32 v12, v0
	v_mov_b32_e32 v13, v0
	v_mov_b32_e32 v14, v0
	v_mov_b32_e32 v15, v0
	s_nop 0
	ds_read_b128 v[16:19], v215 offset:24576
	ds_read_b128 v[68:71], v215 offset:32768
	s_waitcnt lgkmcnt(0)
	v_mfma_f32_32x32x16_bf16 v[48:63], v[16:19], v[64:67], v[0:15]
	ds_read_b128 v[16:19], v215 offset:28672
	s_waitcnt lgkmcnt(0)
	v_mfma_f32_32x32x16_bf16 v[32:47], v[16:19], v[64:67], v[0:15]
	v_mfma_f32_32x32x16_bf16 v[16:31], v[68:71], v[64:67], v[0:15]
	ds_read_b128 v[68:71], v215 offset:36864
	s_waitcnt lgkmcnt(0)
	v_mfma_f32_32x32x16_bf16 v[0:15], v[68:71], v[64:67], v[0:15]
	s_nop 0
	s_add_i32 s29, s29, s44
	v_add_u32_e32 v64, s29, v73
	v_ashrrev_i32_e32 v65, 31, v64
	v_lshlrev_b64 v[64:65], 12, v[64:65]
	v_lshl_add_u64 v[182:183], v[154:155], 0, v[64:65]
	v_add_u32_e32 v64, s29, v74
	v_ashrrev_i32_e32 v65, 31, v64
	v_lshlrev_b64 v[64:65], 12, v[64:65]
	v_bitop3_b32 v66, v75, 7, v170 bitop3:0x48
	v_lshl_or_b32 v64, v66, 4, v64
	v_lshlrev_b32_e32 v150, 6, v176
	v_lshlrev_b32_e32 v188, 6, v166
	v_mov_b32_e32 v189, v151
	v_lshlrev_b32_e32 v192, 6, v162
	v_mov_b32_e32 v193, v151
	v_lshl_add_u64 v[184:185], s[18:19], 0, v[64:65]
	v_lshl_add_u64 v[186:187], v[168:169], 0, v[150:151]
	v_lshl_add_u64 v[190:191], v[164:165], 0, v[188:189]
	v_lshl_add_u64 v[194:195], v[160:161], 0, v[192:193]
	s_mov_b32 s29, -3
	s_waitcnt vmcnt(0)
	s_barrier
; __device__ __forceinline__ void attn_unit(LAS unsigned char* lds, const bf16_t* Q, const bf16_t* KN, const bf16_t* KPE, const bf16_t* VT, bf16_t* Y, float* ssq_b, int b, int h, int qg) {
;     ...
;         if (j + 1 < ntiles) AT_DMA(j + 1);
;         if (j <= cw) {
;             const LAS unsigned char* kb = lds + (j & 1) * KV_BYTES; const LAS unsigned char* vb = kb + KS_BYTES;
;             f32x16 s0, s1;
; #pragma unroll
;             for (int i = 0; i < 16; ++i) { s0[i] = 0.f; s1[i] = 0.f; }
;             __builtin_amdgcn_s_setprio(1);
;             {
;                 bf16x8 a0n = *(const LAS bf16x8*)(kb + kbase0), a1n = *(const LAS bf16x8*)(kb + (kbase0 + 32u * 384u));
; #pragma unroll
;                 for (int ks = 0; ks < 12; ++ks) {
;                     const bf16x8 a0 = a0n, a1 = a1n;
;                     if (ks + 1 < 12) { const unsigned off = (kbase0 ^ (unsigned)(((2 * (ks + 1)) & 7) << 4)) + (unsigned)(((2 * (ks + 1)) & 24) << 4);
;                         a0n = *(const LAS bf16x8*)(kb + off); a1n = *(const LAS bf16x8*)(kb + (off + 32u * 384u)); }
;                     s0 = __builtin_amdgcn_mfma_f32_32x32x16_bf16(a0, qf[ks], s0, 0, 0, 0);
;                     s1 = __builtin_amdgcn_mfma_f32_32x32x16_bf16(a1, qf[ks], s1, 0, 0, 0);
;                 }
;             }
;             __builtin_amdgcn_s_setprio(0);
;             if (j == 0) {
; #pragma unroll
;                 for (int i = 0; i < 16; ++i) { if (i >= 8) s0[i] = -INFINITY; s1[i] = -INFINITY; }
;             }
;             float mx = s0[0];
; #pragma unroll
;             for (int i = 1; i < 16; ++i) mx = fmaxf(mx, s0[i]);
; #pragma unroll
;             for (int i = 0; i < 16; ++i) mx = fmaxf(mx, s1[i]);
;             mx = fmaxf(mx, __shfl_xor(mx, 32));
;             const bool upd = __builtin_amdgcn_ballot_w64(mx - mrun > 8.0f) != 0ull;
;             const float mn = upd ? fmaxf(mrun, mx) : mrun; const float alpha = upd ? fexp2(mrun - mn) : 1.0f; mrun = mn;
;             s0 = s0 - mn; s1 = s1 - mn;
; #pragma unroll
;             for (int i = 0; i < 16; ++i) { s0[i] = fexp2(s0[i]); s1[i] = fexp2(s1[i]); }
;             const f32x16 t16 = s0 + s1;
;             typedef float f32x8_ __attribute__((ext_vector_type(8)));
;             const f32x8_ t8 = __builtin_shufflevector(t16, t16, 0, 1, 2, 3, 4, 5, 6, 7) + __builtin_shufflevector(t16, t16, 8, 9, 10, 11, 12, 13, 14, 15);
.LBB0_693:
	s_add_i32 s44, s29, 4
	s_bitcmp1_b32 s29, 0
	s_cselect_b32 s6, 0, 0xa000
	s_add_i32 s6, s6, 0
	s_add_i32 m0, s6, s7
	s_add_i32 s45, s6, s54
	global_load_lds_dwordx4 v[194:195], off
	s_add_i32 m0, s6, s8
	s_nop 0
	global_load_lds_dwordx4 v[190:191], off
	s_add_i32 m0, s6, s9
	s_nop 0
	global_load_lds_dwordx4 v[186:187], off
	s_add_i32 m0, s45, 0x6000
	s_nop 0
	global_load_lds_dwordx4 v[182:183], off
	s_add_i32 m0, s45, 0x6400
	s_cmp_gt_u32 s44, s10
	global_load_lds_dwordx4 v[184:185], off
	s_cbranch_scc1 .LBB0_697
	s_bitcmp1_b32 s44, 0
	s_cselect_b32 s44, 0xa000, 0
	s_add_i32 s44, s44, 0
	s_nop 0
	v_add_u32_e32 v159, s44, v197
	v_add_u32_e32 v167, s44, v199
	v_add_u32_e32 v177, s44, v200
	v_add_u32_e32 v196, s44, v201
	ds_read_b128 v[208:211], v159
	ds_read_b128 v[214:217], v159 offset:12288
	ds_read_b128 v[218:221], v167
	ds_read_b128 v[222:225], v167 offset:12288
	ds_read_b128 v[244:247], v177
	ds_read_b128 v[248:251], v177 offset:12288
	s_waitcnt lgkmcnt(4)
	v_mfma_f32_32x32x16_bf16 v[80:95], v[208:211], v[140:143], 0
	v_mfma_f32_32x32x16_bf16 v[64:79], v[214:217], v[140:143], 0
	ds_read_b128 v[208:211], v196
	ds_read_b128 v[214:217], v196 offset:12288
	s_waitcnt lgkmcnt(4)
	v_mfma_f32_32x32x16_bf16 v[80:95], v[218:221], v[136:139], v[80:95]
	v_mfma_f32_32x32x16_bf16 v[64:79], v[222:225], v[136:139], v[64:79]
	ds_read_b128 v[218:221], v159 offset:128
	ds_read_b128 v[222:225], v159 offset:12416
	s_waitcnt lgkmcnt(4)
	v_mfma_f32_32x32x16_bf16 v[80:95], v[244:247], v[132:135], v[80:95]
	v_mfma_f32_32x32x16_bf16 v[64:79], v[248:251], v[132:135], v[64:79]
	ds_read_b128 v[244:247], v167 offset:128
	ds_read_b128 v[248:251], v167 offset:12416
	s_waitcnt lgkmcnt(4)
	v_mfma_f32_32x32x16_bf16 v[80:95], v[208:211], v[128:131], v[80:95]
	v_mfma_f32_32x32x16_bf16 v[64:79], v[214:217], v[128:131], v[64:79]
	ds_read_b128 v[208:211], v177 offset:128
	ds_read_b128 v[214:217], v177 offset:12416
	s_waitcnt lgkmcnt(4)
	v_mfma_f32_32x32x16_bf16 v[80:95], v[218:221], v[124:127], v[80:95]
	v_mfma_f32_32x32x16_bf16 v[64:79], v[222:225], v[124:127], v[64:79]
	ds_read_b128 v[218:221], v196 offset:128
	ds_read_b128 v[222:225], v196 offset:12416
	s_waitcnt lgkmcnt(4)
	v_mfma_f32_32x32x16_bf16 v[80:95], v[244:247], v[120:123], v[80:95]
	v_mfma_f32_32x32x16_bf16 v[64:79], v[248:251], v[120:123], v[64:79]
	ds_read_b128 v[244:247], v159 offset:256
	ds_read_b128 v[248:251], v159 offset:12544
	s_waitcnt lgkmcnt(4)
	v_mfma_f32_32x32x16_bf16 v[80:95], v[208:211], v[116:119], v[80:95]
	v_mfma_f32_32x32x16_bf16 v[64:79], v[214:217], v[116:119], v[64:79]
	ds_read_b128 v[208:211], v167 offset:256
	ds_read_b128 v[214:217], v167 offset:12544
	s_waitcnt lgkmcnt(4)
	v_mfma_f32_32x32x16_bf16 v[80:95], v[218:221], v[112:115], v[80:95]
	v_mfma_f32_32x32x16_bf16 v[64:79], v[222:225], v[112:115], v[64:79]
	ds_read_b128 v[218:221], v177 offset:256
	ds_read_b128 v[222:225], v177 offset:12544
	s_waitcnt lgkmcnt(4)
	v_mfma_f32_32x32x16_bf16 v[80:95], v[244:247], v[108:111], v[80:95]
	v_mfma_f32_32x32x16_bf16 v[64:79], v[248:251], v[108:111], v[64:79]
	ds_read_b128 v[244:247], v196 offset:256
	ds_read_b128 v[248:251], v196 offset:12544
	s_waitcnt lgkmcnt(4)
	v_mfma_f32_32x32x16_bf16 v[80:95], v[208:211], v[104:107], v[80:95]
	v_mfma_f32_32x32x16_bf16 v[64:79], v[214:217], v[104:107], v[64:79]
	s_waitcnt lgkmcnt(2)
	v_mfma_f32_32x32x16_bf16 v[80:95], v[218:221], v[100:103], v[80:95]
	v_mfma_f32_32x32x16_bf16 v[64:79], v[222:225], v[100:103], v[64:79]
	s_waitcnt lgkmcnt(0)
	v_mfma_f32_32x32x16_bf16 v[80:95], v[244:247], v[96:99], v[80:95]
	v_mfma_f32_32x32x16_bf16 v[64:79], v[248:251], v[96:99], v[64:79]
	v_add_u32_e32 v252, s44, v198
	v_add_u32_e32 v253, s44, v202
	v_add_u32_e32 v254, s44, v203
	v_add_u32_e32 v255, s44, v204
	ds_read_b128 v[244:247], v252 offset:24576
	ds_read_b128 v[248:251], v252 offset:28672
	s_nop 0
	s_nop 7
	v_max_f32_e32 v159, v81, v81
	v_max_f32_e32 v167, v80, v80
	v_max_f32_e32 v159, v167, v159
	v_max3_f32 v159, v159, v82, v83
	v_max3_f32 v159, v159, v84, v85
	v_max3_f32 v159, v159, v86, v87
	v_max3_f32 v159, v159, v88, v89
	v_max3_f32 v159, v159, v90, v91
	v_max3_f32 v159, v159, v92, v93
	v_max3_f32 v159, v159, v94, v95
	v_max3_f32 v159, v159, v64, v65
	v_max3_f32 v159, v159, v66, v67
	v_max3_f32 v159, v159, v68, v69
	v_max3_f32 v159, v159, v70, v71
	v_max3_f32 v159, v159, v72, v73
	v_max3_f32 v159, v159, v74, v75
	v_max3_f32 v159, v159, v76, v77
	v_max3_f32 v159, v159, v78, v79
	ds_bpermute_b32 v167, v205, v159
	s_waitcnt lgkmcnt(0)
	v_max_f32_e32 v167, v167, v167
	v_max_f32_e32 v159, v159, v167
	v_sub_f32_e32 v167, v159, v163
	v_cmp_lt_f32_e32 vcc, s38, v167
	s_cmp_eq_u64 vcc, 0
	v_max_f32_e32 v167, v163, v163
	s_cselect_b64 s[52:53], -1, 0
	v_max_f32_e32 v159, v167, v159
	v_cndmask_b32_e64 v159, v159, v163, s[52:53]
	v_sub_f32_e32 v163, v163, v159
	v_exp_f32_e32 v196, v163
	s_cbranch_vccz .LBB0_696
	v_pk_mul_f32 v[62:63], v[62:63], v[196:197] op_sel_hi:[1,0]
	v_pk_mul_f32 v[60:61], v[60:61], v[196:197] op_sel_hi:[1,0]
	v_pk_mul_f32 v[58:59], v[58:59], v[196:197] op_sel_hi:[1,0]
	v_pk_mul_f32 v[56:57], v[56:57], v[196:197] op_sel_hi:[1,0]
	v_pk_mul_f32 v[54:55], v[54:55], v[196:197] op_sel_hi:[1,0]
	v_pk_mul_f32 v[52:53], v[52:53], v[196:197] op_sel_hi:[1,0]
	v_pk_mul_f32 v[50:51], v[50:51], v[196:197] op_sel_hi:[1,0]
	v_pk_mul_f32 v[48:49], v[48:49], v[196:197] op_sel_hi:[1,0]
	v_pk_mul_f32 v[46:47], v[46:47], v[196:197] op_sel_hi:[1,0]
	v_pk_mul_f32 v[44:45], v[44:45], v[196:197] op_sel_hi:[1,0]
	v_pk_mul_f32 v[42:43], v[42:43], v[196:197] op_sel_hi:[1,0]
	v_pk_mul_f32 v[40:41], v[40:41], v[196:197] op_sel_hi:[1,0]
	v_pk_mul_f32 v[38:39], v[38:39], v[196:197] op_sel_hi:[1,0]
	v_pk_mul_f32 v[36:37], v[36:37], v[196:197] op_sel_hi:[1,0]
	v_pk_mul_f32 v[34:35], v[34:35], v[196:197] op_sel_hi:[1,0]
	v_pk_mul_f32 v[32:33], v[32:33], v[196:197] op_sel_hi:[1,0]
	v_pk_mul_f32 v[30:31], v[30:31], v[196:197] op_sel_hi:[1,0]
	v_pk_mul_f32 v[28:29], v[28:29], v[196:197] op_sel_hi:[1,0]
	v_pk_mul_f32 v[26:27], v[26:27], v[196:197] op_sel_hi:[1,0]
	v_pk_mul_f32 v[24:25], v[24:25], v[196:197] op_sel_hi:[1,0]
	v_pk_mul_f32 v[22:23], v[22:23], v[196:197] op_sel_hi:[1,0]
	v_pk_mul_f32 v[20:21], v[20:21], v[196:197] op_sel_hi:[1,0]
	v_pk_mul_f32 v[18:19], v[18:19], v[196:197] op_sel_hi:[1,0]
	v_pk_mul_f32 v[16:17], v[16:17], v[196:197] op_sel_hi:[1,0]
	v_pk_mul_f32 v[14:15], v[14:15], v[196:197] op_sel_hi:[1,0]
	v_pk_mul_f32 v[12:13], v[12:13], v[196:197] op_sel_hi:[1,0]
	v_pk_mul_f32 v[10:11], v[10:11], v[196:197] op_sel_hi:[1,0]
	v_pk_mul_f32 v[8:9], v[8:9], v[196:197] op_sel_hi:[1,0]
	v_pk_mul_f32 v[6:7], v[6:7], v[196:197] op_sel_hi:[1,0]
	v_pk_mul_f32 v[4:5], v[4:5], v[196:197] op_sel_hi:[1,0]
	v_pk_mul_f32 v[2:3], v[2:3], v[196:197] op_sel_hi:[1,0]
	v_pk_mul_f32 v[0:1], v[0:1], v[196:197] op_sel_hi:[1,0]
; #define LAS __attribute__((address_space(3)))
; __device__ __forceinline__ void attn_unit(LAS unsigned char* lds, const bf16_t* Q, const bf16_t* KN, const bf16_t* KPE, const bf16_t* VT, bf16_t* Y, float* ssq_b, int b, int h, int qg) {
;     ...
;             const float mn = upd ? fmaxf(mrun, mx) : mrun; const float alpha = upd ? fexp2(mrun - mn) : 1.0f; mrun = mn;
;             s0 = s0 - mn; s1 = s1 - mn;
; #pragma unroll
;             for (int i = 0; i < 16; ++i) { s0[i] = fexp2(s0[i]); s1[i] = fexp2(s1[i]); }
;             const f32x16 t16 = s0 + s1;
;             typedef float f32x8_ __attribute__((ext_vector_type(8)));
;             const f32x8_ t8 = __builtin_shufflevector(t16, t16, 0, 1, 2, 3, 4, 5, 6, 7) + __builtin_shufflevector(t16, t16, 8, 9, 10, 11, 12, 13, 14, 15);
;             const f32x4 t4 = __builtin_shufflevector(t8, t8, 0, 1, 2, 3) + __builtin_shufflevector(t8, t8, 4, 5, 6, 7);
;             const float ps = (t4[0] + t4[1]) + (t4[2] + t4[3]);
;             lsum = lsum * alpha + ps;
;             if (upd) {
; #pragma unroll
;                 for (int d = 0; d < 4; ++d)
; #pragma unroll
;                     for (int i = 0; i < 16; ++i) o[d][i] *= alpha;
;             }
; #pragma unroll
;             for (int kb2 = 0; kb2 < 2; ++kb2)
; #pragma unroll
;                 for (int a = 0; a < 2; ++a) {
;                     u32x4 pw;
;                     if (kb2 == 0) { pw.x = cvt_pk(s0[8 * a + 0], s0[8 * a + 1]); pw.y = cvt_pk(s0[8 * a + 2], s0[8 * a + 3]); pw.z = cvt_pk(s0[8 * a + 4], s0[8 * a + 5]); pw.w = cvt_pk(s0[8 * a + 6], s0[8 * a + 7]); }
;                     else { pw.x = cvt_pk(s1[8 * a + 0], s1[8 * a + 1]); pw.y = cvt_pk(s1[8 * a + 2], s1[8 * a + 3]); pw.z = cvt_pk(s1[8 * a + 4], s1[8 * a + 5]); pw.w = cvt_pk(s1[8 * a + 6], s1[8 * a + 7]); }
;                     const bf16x8 pf = __builtin_bit_cast(bf16x8, pw);
;                     const unsigned vro = vbase0 ^ (unsigned)((4 * kb2 + 2 * a) << 4);
;                     __builtin_amdgcn_s_setprio(1);
; #pragma unroll
;                     for (int db = 0; db < 4; ++db) {
;                         const bf16x8 vf = *(const LAS bf16x8*)(vb + (vro + (unsigned)(db * 4096)));
;                         o[db] = __builtin_amdgcn_mfma_f32_32x32x16_bf16(vf, pf, o[db], 0, 0, 0);
;                     }
;                     __builtin_amdgcn_s_setprio(0);
;                 }
.LBB0_696:
	v_sub_f32_e32 v95, v95, v159
	v_sub_f32_e32 v94, v94, v159
	v_sub_f32_e32 v93, v93, v159
	v_sub_f32_e32 v92, v92, v159
	v_sub_f32_e32 v91, v91, v159
	v_sub_f32_e32 v90, v90, v159
	v_sub_f32_e32 v89, v89, v159
	v_sub_f32_e32 v88, v88, v159
	v_sub_f32_e32 v87, v87, v159
	v_sub_f32_e32 v86, v86, v159
	v_sub_f32_e32 v85, v85, v159
	v_sub_f32_e32 v84, v84, v159
	v_sub_f32_e32 v83, v83, v159
	v_sub_f32_e32 v82, v82, v159
	v_sub_f32_e32 v81, v81, v159
	v_sub_f32_e32 v80, v80, v159
	v_sub_f32_e32 v163, v79, v159
	v_sub_f32_e32 v167, v78, v159
	v_sub_f32_e32 v177, v77, v159
	v_sub_f32_e32 v207, v76, v159
	v_sub_f32_e32 v208, v75, v159
	v_sub_f32_e32 v209, v74, v159
	v_sub_f32_e32 v210, v73, v159
	v_sub_f32_e32 v211, v72, v159
	v_sub_f32_e32 v79, v71, v159
	v_sub_f32_e32 v71, v70, v159
	v_sub_f32_e32 v70, v69, v159
	v_sub_f32_e32 v69, v68, v159
	v_sub_f32_e32 v68, v67, v159
	v_sub_f32_e32 v67, v66, v159
	v_sub_f32_e32 v66, v65, v159
	v_sub_f32_e32 v65, v64, v159
	v_exp_f32_e32 v64, v80
	v_exp_f32_e32 v72, v65
	v_exp_f32_e32 v65, v81
	v_exp_f32_e32 v73, v66
	v_exp_f32_e32 v66, v82
	v_exp_f32_e32 v74, v67
	v_exp_f32_e32 v67, v83
	v_exp_f32_e32 v75, v68
	v_exp_f32_e32 v68, v84
	v_exp_f32_e32 v76, v69
	v_exp_f32_e32 v69, v85
	v_exp_f32_e32 v77, v70
	v_exp_f32_e32 v70, v86
	v_exp_f32_e32 v78, v71
	v_exp_f32_e32 v71, v87
	v_exp_f32_e32 v79, v79
	v_exp_f32_e32 v80, v88
	v_exp_f32_e32 v82, v211
	v_exp_f32_e32 v81, v89
	v_exp_f32_e32 v83, v210
	v_exp_f32_e32 v84, v90
	v_exp_f32_e32 v86, v209
	v_exp_f32_e32 v85, v91
	v_exp_f32_e32 v87, v208
	v_exp_f32_e32 v88, v92
	v_exp_f32_e32 v90, v207
	v_exp_f32_e32 v89, v93
	v_exp_f32_e32 v91, v177
	v_exp_f32_e32 v92, v94
	v_exp_f32_e32 v94, v167
	v_exp_f32_e32 v93, v95
	v_exp_f32_e32 v95, v163
	v_pk_add_f32 v[208:209], v[86:87], v[84:85]
	v_pk_add_f32 v[210:211], v[74:75], v[66:67]
	v_pk_add_f32 v[216:217], v[78:79], v[70:71]
	v_pk_add_f32 v[214:215], v[94:95], v[92:93]
	v_pk_add_f32 v[218:219], v[82:83], v[80:81]
	v_pk_add_f32 v[220:221], v[72:73], v[64:65]
	v_pk_add_f32 v[222:223], v[90:91], v[88:89]
	v_pk_add_f32 v[224:225], v[76:77], v[68:69]
	v_pk_add_f32 v[218:219], v[220:221], v[218:219]
	v_pk_add_f32 v[222:223], v[224:225], v[222:223]
	v_pk_add_f32 v[214:215], v[216:217], v[214:215]
	v_pk_add_f32 v[208:209], v[210:211], v[208:209]
	v_pk_add_f32 v[210:211], v[218:219], v[222:223]
	v_pk_add_f32 v[208:209], v[208:209], v[214:215]
	v_add_f32_e32 v167, v210, v211
	v_add_f32_e32 v177, v208, v209
	v_cndmask_b32_e64 v163, v196, 1.0, s[52:53]
	v_add_f32_e32 v167, v167, v177
	v_fmac_f32_e32 v167, v157, v163
	ds_read_b128 v[208:211], v252 offset:32768
	ds_read_b128 v[214:217], v252 offset:36864
	ds_read_b128 v[218:221], v253 offset:24576
	ds_read_b128 v[222:225], v253 offset:28672
	v_cvt_pk_bf16_f32 v64, v64, v65
	v_cvt_pk_bf16_f32 v65, v66, v67
	v_cvt_pk_bf16_f32 v66, v68, v69
	v_cvt_pk_bf16_f32 v67, v70, v71
	s_nop 0
	s_waitcnt lgkmcnt(5)
	v_mfma_f32_32x32x16_bf16 v[48:63], v[244:247], v[64:67], v[48:63]
	ds_read_b128 v[244:247], v253 offset:32768
	s_waitcnt lgkmcnt(5)
	v_mfma_f32_32x32x16_bf16 v[32:47], v[248:251], v[64:67], v[32:47]
	ds_read_b128 v[248:251], v253 offset:36864
	s_waitcnt lgkmcnt(5)
	v_mfma_f32_32x32x16_bf16 v[16:31], v[208:211], v[64:67], v[16:31]
	ds_read_b128 v[208:211], v254 offset:24576
	s_waitcnt lgkmcnt(5)
	v_mfma_f32_32x32x16_bf16 v[0:15], v[214:217], v[64:67], v[0:15]
	ds_read_b128 v[214:217], v254 offset:28672
	s_nop 0
	v_cvt_pk_bf16_f32 v64, v80, v81
	v_cvt_pk_bf16_f32 v65, v84, v85
	v_cvt_pk_bf16_f32 v66, v88, v89
	v_cvt_pk_bf16_f32 v67, v92, v93
	s_nop 0
	s_waitcnt lgkmcnt(5)
	v_mfma_f32_32x32x16_bf16 v[48:63], v[218:221], v[64:67], v[48:63]
	ds_read_b128 v[218:221], v254 offset:32768
	s_waitcnt lgkmcnt(5)
	v_mfma_f32_32x32x16_bf16 v[32:47], v[222:225], v[64:67], v[32:47]
	ds_read_b128 v[222:225], v254 offset:36864
	s_waitcnt lgkmcnt(5)
	v_mfma_f32_32x32x16_bf16 v[16:31], v[244:247], v[64:67], v[16:31]
	ds_read_b128 v[244:247], v255 offset:24576
	s_waitcnt lgkmcnt(5)
	v_mfma_f32_32x32x16_bf16 v[0:15], v[248:251], v[64:67], v[0:15]
	ds_read_b128 v[248:251], v255 offset:28672
	s_nop 0
	v_cvt_pk_bf16_f32 v64, v72, v73
	v_cvt_pk_bf16_f32 v65, v74, v75
	v_cvt_pk_bf16_f32 v66, v76, v77
	v_cvt_pk_bf16_f32 v67, v78, v79
	s_nop 0
	s_waitcnt lgkmcnt(5)
	v_mfma_f32_32x32x16_bf16 v[48:63], v[208:211], v[64:67], v[48:63]
	ds_read_b128 v[208:211], v255 offset:32768
	s_waitcnt lgkmcnt(5)
	v_mfma_f32_32x32x16_bf16 v[32:47], v[214:217], v[64:67], v[32:47]
	ds_read_b128 v[214:217], v255 offset:36864
	s_waitcnt lgkmcnt(5)
	v_mfma_f32_32x32x16_bf16 v[16:31], v[218:221], v[64:67], v[16:31]
	s_waitcnt lgkmcnt(4)
	v_mfma_f32_32x32x16_bf16 v[0:15], v[222:225], v[64:67], v[0:15]
	s_nop 0
	v_cvt_pk_bf16_f32 v64, v82, v83
	v_cvt_pk_bf16_f32 v65, v86, v87
	v_cvt_pk_bf16_f32 v66, v90, v91
	v_cvt_pk_bf16_f32 v67, v94, v95
	s_nop 0
	s_waitcnt lgkmcnt(3)
	v_mfma_f32_32x32x16_bf16 v[48:63], v[244:247], v[64:67], v[48:63]
	s_waitcnt lgkmcnt(2)
	v_mfma_f32_32x32x16_bf16 v[32:47], v[248:251], v[64:67], v[32:47]
	s_waitcnt lgkmcnt(1)
	v_mfma_f32_32x32x16_bf16 v[16:31], v[208:211], v[64:67], v[16:31]
	s_waitcnt lgkmcnt(0)
	v_mfma_f32_32x32x16_bf16 v[0:15], v[214:217], v[64:67], v[0:15]
	s_nop 0
	v_mov_b32_e32 v157, v167
	s_branch .LBB0_698

; #define LAS __attribute__((address_space(3)))
; __device__ __forceinline__ void attn_unit(LAS unsigned char* lds, const bf16_t* Q, const bf16_t* KN, const bf16_t* KPE, const bf16_t* VT, bf16_t* Y, float* ssq_b, int b, int h, int qg) {
;     ...
;         if (j <= cw) {
;             const LAS unsigned char* kb = lds + (j & 1) * KV_BYTES; const LAS unsigned char* vb = kb + KS_BYTES;
;             f32x16 s0, s1;
; #pragma unroll
;             for (int i = 0; i < 16; ++i) { s0[i] = 0.f; s1[i] = 0.f; }
;             __builtin_amdgcn_s_setprio(1);
;             {
;                 bf16x8 a0n = *(const LAS bf16x8*)(kb + kbase0), a1n = *(const LAS bf16x8*)(kb + (kbase0 + 32u * 384u));
; #pragma unroll
;                 for (int ks = 0; ks < 12; ++ks) {
;                     const bf16x8 a0 = a0n, a1 = a1n;
;                     if (ks + 1 < 12) { const unsigned off = (kbase0 ^ (unsigned)(((2 * (ks + 1)) & 7) << 4)) + (unsigned)(((2 * (ks + 1)) & 24) << 4);
;                         a0n = *(const LAS bf16x8*)(kb + off); a1n = *(const LAS bf16x8*)(kb + (off + 32u * 384u)); }
;                     s0 = __builtin_amdgcn_mfma_f32_32x32x16_bf16(a0, qf[ks], s0, 0, 0, 0);
;                     s1 = __builtin_amdgcn_mfma_f32_32x32x16_bf16(a1, qf[ks], s1, 0, 0, 0);
;                 }
;             }
;             __builtin_amdgcn_s_setprio(0);
;             if (j == 0) {
; #pragma unroll
;                 for (int i = 0; i < 16; ++i) { if (i >= 8) s0[i] = -INFINITY; s1[i] = -INFINITY; }
;             }
;             float mx = s0[0];
; #pragma unroll
;             for (int i = 1; i < 16; ++i) mx = fmaxf(mx, s0[i]);
; #pragma unroll
;             for (int i = 0; i < 16; ++i) mx = fmaxf(mx, s1[i]);
;             mx = fmaxf(mx, __shfl_xor(mx, 32));
;             const bool upd = __builtin_amdgcn_ballot_w64(mx - mrun > 8.0f) != 0ull;
;             const float mn = upd ? fmaxf(mrun, mx) : mrun; const float alpha = upd ? fexp2(mrun - mn) : 1.0f; mrun = mn;
;             s0 = s0 - mn; s1 = s1 - mn;
; #pragma unroll
;             for (int i = 0; i < 16; ++i) { s0[i] = fexp2(s0[i]); s1[i] = fexp2(s1[i]); }
;             const f32x16 t16 = s0 + s1;
;             typedef float f32x8_ __attribute__((ext_vector_type(8)));
;             const f32x8_ t8 = __builtin_shufflevector(t16, t16, 0, 1, 2, 3, 4, 5, 6, 7) + __builtin_shufflevector(t16, t16, 8, 9, 10, 11, 12, 13, 14, 15);
.LBB0_702:
	s_cmp_ge_u32 s11, s10
	s_cbranch_scc1 .LBB0_706
	s_nop 0
	v_add_u32_e32 v150, s6, v197
	v_add_u32_e32 v160, s6, v199
	v_add_u32_e32 v161, s6, v200
	v_add_u32_e32 v252, s6, v201
	ds_read_b128 v[208:211], v150
	ds_read_b128 v[214:217], v150 offset:12288
	ds_read_b128 v[218:221], v160
	ds_read_b128 v[222:225], v160 offset:12288
	ds_read_b128 v[244:247], v161
	ds_read_b128 v[248:251], v161 offset:12288
	s_waitcnt lgkmcnt(5)
	v_mfma_f32_32x32x16_bf16 v[80:95], v[208:211], v[140:143], 0
	ds_read_b128 v[208:211], v252
	s_waitcnt lgkmcnt(5)
	v_mfma_f32_32x32x16_bf16 v[64:79], v[214:217], v[140:143], 0
	ds_read_b128 v[214:217], v252 offset:12288
	s_waitcnt lgkmcnt(5)
	v_mfma_f32_32x32x16_bf16 v[80:95], v[218:221], v[136:139], v[80:95]
	ds_read_b128 v[218:221], v150 offset:128
	s_waitcnt lgkmcnt(5)
	v_mfma_f32_32x32x16_bf16 v[64:79], v[222:225], v[136:139], v[64:79]
	ds_read_b128 v[222:225], v150 offset:12416
	s_waitcnt lgkmcnt(5)
	v_mfma_f32_32x32x16_bf16 v[80:95], v[244:247], v[132:135], v[80:95]
	ds_read_b128 v[244:247], v160 offset:128
	s_waitcnt lgkmcnt(5)
	v_mfma_f32_32x32x16_bf16 v[64:79], v[248:251], v[132:135], v[64:79]
	ds_read_b128 v[248:251], v160 offset:12416
	s_waitcnt lgkmcnt(5)
	v_mfma_f32_32x32x16_bf16 v[80:95], v[208:211], v[128:131], v[80:95]
	ds_read_b128 v[208:211], v161 offset:128
	s_waitcnt lgkmcnt(5)
	v_mfma_f32_32x32x16_bf16 v[64:79], v[214:217], v[128:131], v[64:79]
	ds_read_b128 v[214:217], v161 offset:12416
	s_waitcnt lgkmcnt(5)
	v_mfma_f32_32x32x16_bf16 v[80:95], v[218:221], v[124:127], v[80:95]
	ds_read_b128 v[218:221], v252 offset:128
	s_waitcnt lgkmcnt(5)
	v_mfma_f32_32x32x16_bf16 v[64:79], v[222:225], v[124:127], v[64:79]
	ds_read_b128 v[222:225], v252 offset:12416
	s_waitcnt lgkmcnt(5)
	v_mfma_f32_32x32x16_bf16 v[80:95], v[244:247], v[120:123], v[80:95]
	ds_read_b128 v[244:247], v150 offset:256
	s_waitcnt lgkmcnt(5)
	v_mfma_f32_32x32x16_bf16 v[64:79], v[248:251], v[120:123], v[64:79]
	ds_read_b128 v[248:251], v150 offset:12544
	s_waitcnt lgkmcnt(5)
	v_mfma_f32_32x32x16_bf16 v[80:95], v[208:211], v[116:119], v[80:95]
	ds_read_b128 v[208:211], v160 offset:256
	s_waitcnt lgkmcnt(5)
	v_mfma_f32_32x32x16_bf16 v[64:79], v[214:217], v[116:119], v[64:79]
	ds_read_b128 v[214:217], v160 offset:12544
	s_waitcnt lgkmcnt(5)
	v_mfma_f32_32x32x16_bf16 v[80:95], v[218:221], v[112:115], v[80:95]
	ds_read_b128 v[218:221], v161 offset:256
	s_waitcnt lgkmcnt(5)
	v_mfma_f32_32x32x16_bf16 v[64:79], v[222:225], v[112:115], v[64:79]
	ds_read_b128 v[222:225], v161 offset:12544
	s_waitcnt lgkmcnt(5)
	v_mfma_f32_32x32x16_bf16 v[80:95], v[244:247], v[108:111], v[80:95]
	ds_read_b128 v[244:247], v252 offset:256
	s_waitcnt lgkmcnt(5)
	v_mfma_f32_32x32x16_bf16 v[64:79], v[248:251], v[108:111], v[64:79]
	ds_read_b128 v[248:251], v252 offset:12544
	s_waitcnt lgkmcnt(5)
	v_mfma_f32_32x32x16_bf16 v[80:95], v[208:211], v[104:107], v[80:95]
	s_waitcnt lgkmcnt(4)
	v_mfma_f32_32x32x16_bf16 v[64:79], v[214:217], v[104:107], v[64:79]
	s_waitcnt lgkmcnt(3)
	v_mfma_f32_32x32x16_bf16 v[80:95], v[218:221], v[100:103], v[80:95]
	s_waitcnt lgkmcnt(2)
	v_mfma_f32_32x32x16_bf16 v[64:79], v[222:225], v[100:103], v[64:79]
	s_waitcnt lgkmcnt(1)
	v_mfma_f32_32x32x16_bf16 v[80:95], v[244:247], v[96:99], v[80:95]
	s_waitcnt lgkmcnt(0)
	v_mfma_f32_32x32x16_bf16 v[64:79], v[248:251], v[96:99], v[64:79]
	s_nop 0
	s_nop 8
	v_max_f32_e32 v96, v81, v81
	v_max_f32_e32 v97, v80, v80
	v_max_f32_e32 v96, v97, v96
	v_max3_f32 v96, v96, v82, v83
	v_max3_f32 v96, v96, v84, v85
	v_max3_f32 v96, v96, v86, v87
	v_max3_f32 v96, v96, v88, v89
	v_max3_f32 v96, v96, v90, v91
	v_max3_f32 v96, v96, v92, v93
	v_max3_f32 v96, v96, v94, v95
	v_max3_f32 v96, v96, v64, v65
	v_max3_f32 v96, v96, v66, v67
	v_max3_f32 v96, v96, v68, v69
	v_max3_f32 v96, v96, v70, v71
	v_max3_f32 v96, v96, v72, v73
	v_max3_f32 v96, v96, v74, v75
	v_max3_f32 v96, v96, v76, v77
	v_max3_f32 v96, v96, v78, v79
	ds_bpermute_b32 v97, v205, v96
	s_waitcnt lgkmcnt(0)
	v_max_f32_e32 v97, v97, v97
	v_max_f32_e32 v96, v96, v97
	v_sub_f32_e32 v97, v96, v159
	v_cmp_lt_f32_e32 vcc, s38, v97
	s_cmp_eq_u64 vcc, 0
	v_max_f32_e32 v97, v159, v159
	s_cselect_b64 s[52:53], -1, 0
	v_max_f32_e32 v96, v97, v96
	v_cndmask_b32_e64 v97, v96, v159, s[52:53]
	v_sub_f32_e32 v96, v159, v97
	v_exp_f32_e32 v96, v96
	s_and_b64 vcc, exec, s[52:53]
	s_cbranch_vccnz .LBB0_705
	v_pk_mul_f32 v[62:63], v[62:63], v[96:97] op_sel_hi:[1,0]
	v_pk_mul_f32 v[60:61], v[60:61], v[96:97] op_sel_hi:[1,0]
	v_pk_mul_f32 v[58:59], v[58:59], v[96:97] op_sel_hi:[1,0]
	v_pk_mul_f32 v[56:57], v[56:57], v[96:97] op_sel_hi:[1,0]
	v_pk_mul_f32 v[54:55], v[54:55], v[96:97] op_sel_hi:[1,0]
	v_pk_mul_f32 v[52:53], v[52:53], v[96:97] op_sel_hi:[1,0]
	v_pk_mul_f32 v[50:51], v[50:51], v[96:97] op_sel_hi:[1,0]
	v_pk_mul_f32 v[48:49], v[48:49], v[96:97] op_sel_hi:[1,0]
	v_pk_mul_f32 v[46:47], v[46:47], v[96:97] op_sel_hi:[1,0]
	v_pk_mul_f32 v[44:45], v[44:45], v[96:97] op_sel_hi:[1,0]
	v_pk_mul_f32 v[42:43], v[42:43], v[96:97] op_sel_hi:[1,0]
	v_pk_mul_f32 v[40:41], v[40:41], v[96:97] op_sel_hi:[1,0]
	v_pk_mul_f32 v[38:39], v[38:39], v[96:97] op_sel_hi:[1,0]
	v_pk_mul_f32 v[36:37], v[36:37], v[96:97] op_sel_hi:[1,0]
	v_pk_mul_f32 v[34:35], v[34:35], v[96:97] op_sel_hi:[1,0]
	v_pk_mul_f32 v[32:33], v[32:33], v[96:97] op_sel_hi:[1,0]
	v_pk_mul_f32 v[30:31], v[30:31], v[96:97] op_sel_hi:[1,0]
	v_pk_mul_f32 v[28:29], v[28:29], v[96:97] op_sel_hi:[1,0]
	v_pk_mul_f32 v[26:27], v[26:27], v[96:97] op_sel_hi:[1,0]
	v_pk_mul_f32 v[24:25], v[24:25], v[96:97] op_sel_hi:[1,0]
	v_pk_mul_f32 v[22:23], v[22:23], v[96:97] op_sel_hi:[1,0]
	v_pk_mul_f32 v[20:21], v[20:21], v[96:97] op_sel_hi:[1,0]
	v_pk_mul_f32 v[18:19], v[18:19], v[96:97] op_sel_hi:[1,0]
	v_pk_mul_f32 v[16:17], v[16:17], v[96:97] op_sel_hi:[1,0]
	v_pk_mul_f32 v[14:15], v[14:15], v[96:97] op_sel_hi:[1,0]
	v_pk_mul_f32 v[12:13], v[12:13], v[96:97] op_sel_hi:[1,0]
	v_pk_mul_f32 v[10:11], v[10:11], v[96:97] op_sel_hi:[1,0]
	v_pk_mul_f32 v[8:9], v[8:9], v[96:97] op_sel_hi:[1,0]
	v_pk_mul_f32 v[6:7], v[6:7], v[96:97] op_sel_hi:[1,0]
	v_pk_mul_f32 v[4:5], v[4:5], v[96:97] op_sel_hi:[1,0]
	v_pk_mul_f32 v[2:3], v[2:3], v[96:97] op_sel_hi:[1,0]
	v_pk_mul_f32 v[0:1], v[0:1], v[96:97] op_sel_hi:[1,0]
; #define LAS __attribute__((address_space(3)))
; __device__ __forceinline__ void attn_unit(LAS unsigned char* lds, const bf16_t* Q, const bf16_t* KN, const bf16_t* KPE, const bf16_t* VT, bf16_t* Y, float* ssq_b, int b, int h, int qg) {
;     ...
;             const float mn = upd ? fmaxf(mrun, mx) : mrun; const float alpha = upd ? fexp2(mrun - mn) : 1.0f; mrun = mn;
;             s0 = s0 - mn; s1 = s1 - mn;
; #pragma unroll
;             for (int i = 0; i < 16; ++i) { s0[i] = fexp2(s0[i]); s1[i] = fexp2(s1[i]); }
;             const f32x16 t16 = s0 + s1;
;             typedef float f32x8_ __attribute__((ext_vector_type(8)));
;             const f32x8_ t8 = __builtin_shufflevector(t16, t16, 0, 1, 2, 3, 4, 5, 6, 7) + __builtin_shufflevector(t16, t16, 8, 9, 10, 11, 12, 13, 14, 15);
;             const f32x4 t4 = __builtin_shufflevector(t8, t8, 0, 1, 2, 3) + __builtin_shufflevector(t8, t8, 4, 5, 6, 7);
;             const float ps = (t4[0] + t4[1]) + (t4[2] + t4[3]);
;             lsum = lsum * alpha + ps;
;             if (upd) {
; #pragma unroll
;                 for (int d = 0; d < 4; ++d)
; #pragma unroll
;                     for (int i = 0; i < 16; ++i) o[d][i] *= alpha;
;             }
; #pragma unroll
;             for (int kb2 = 0; kb2 < 2; ++kb2)
; #pragma unroll
;                 for (int a = 0; a < 2; ++a) {
;                     u32x4 pw;
;                     if (kb2 == 0) { pw.x = cvt_pk(s0[8 * a + 0], s0[8 * a + 1]); pw.y = cvt_pk(s0[8 * a + 2], s0[8 * a + 3]); pw.z = cvt_pk(s0[8 * a + 4], s0[8 * a + 5]); pw.w = cvt_pk(s0[8 * a + 6], s0[8 * a + 7]); }
;                     else { pw.x = cvt_pk(s1[8 * a + 0], s1[8 * a + 1]); pw.y = cvt_pk(s1[8 * a + 2], s1[8 * a + 3]); pw.z = cvt_pk(s1[8 * a + 4], s1[8 * a + 5]); pw.w = cvt_pk(s1[8 * a + 6], s1[8 * a + 7]); }
;                     const bf16x8 pf = __builtin_bit_cast(bf16x8, pw);
;                     const unsigned vro = vbase0 ^ (unsigned)((4 * kb2 + 2 * a) << 4);
;                     __builtin_amdgcn_s_setprio(1);
; #pragma unroll
;                     for (int db = 0; db < 4; ++db) {
;                         const bf16x8 vf = *(const LAS bf16x8*)(vb + (vro + (unsigned)(db * 4096)));
;                         o[db] = __builtin_amdgcn_mfma_f32_32x32x16_bf16(vf, pf, o[db], 0, 0, 0);
;                     }
;                     __builtin_amdgcn_s_setprio(0);
;                 }
.LBB0_705:
	v_sub_f32_e32 v95, v95, v97
	v_sub_f32_e32 v94, v94, v97
	v_sub_f32_e32 v93, v93, v97
	v_sub_f32_e32 v92, v92, v97
	v_sub_f32_e32 v91, v91, v97
	v_sub_f32_e32 v90, v90, v97
	v_sub_f32_e32 v89, v89, v97
	v_sub_f32_e32 v88, v88, v97
	v_sub_f32_e32 v87, v87, v97
	v_sub_f32_e32 v86, v86, v97
	v_sub_f32_e32 v85, v85, v97
	v_sub_f32_e32 v84, v84, v97
	v_sub_f32_e32 v83, v83, v97
	v_sub_f32_e32 v82, v82, v97
	v_sub_f32_e32 v81, v81, v97
	v_sub_f32_e32 v80, v80, v97
	v_sub_f32_e32 v98, v79, v97
	v_sub_f32_e32 v99, v78, v97
	v_sub_f32_e32 v100, v77, v97
	v_sub_f32_e32 v101, v76, v97
	v_sub_f32_e32 v102, v75, v97
	v_sub_f32_e32 v103, v74, v97
	v_sub_f32_e32 v104, v73, v97
	v_sub_f32_e32 v105, v72, v97
	v_sub_f32_e32 v79, v71, v97
	v_sub_f32_e32 v71, v70, v97
	v_sub_f32_e32 v70, v69, v97
	v_sub_f32_e32 v69, v68, v97
	v_sub_f32_e32 v68, v67, v97
	v_sub_f32_e32 v67, v66, v97
	v_sub_f32_e32 v66, v65, v97
	v_sub_f32_e32 v65, v64, v97
	v_exp_f32_e32 v64, v80
	v_exp_f32_e32 v72, v65
	v_exp_f32_e32 v65, v81
	v_exp_f32_e32 v73, v66
	v_exp_f32_e32 v66, v82
	v_exp_f32_e32 v74, v67
	v_exp_f32_e32 v67, v83
	v_exp_f32_e32 v75, v68
	v_exp_f32_e32 v68, v84
	v_exp_f32_e32 v76, v69
	v_exp_f32_e32 v69, v85
	v_exp_f32_e32 v77, v70
	v_exp_f32_e32 v70, v86
	v_exp_f32_e32 v78, v71
	v_exp_f32_e32 v71, v87
	v_exp_f32_e32 v79, v79
	v_exp_f32_e32 v80, v88
	v_exp_f32_e32 v82, v105
	v_exp_f32_e32 v81, v89
	v_exp_f32_e32 v83, v104
	v_exp_f32_e32 v84, v90
	v_exp_f32_e32 v86, v103
	v_exp_f32_e32 v85, v91
	v_exp_f32_e32 v87, v102
	v_exp_f32_e32 v88, v92
	v_exp_f32_e32 v90, v101
	v_exp_f32_e32 v89, v93
	v_exp_f32_e32 v91, v100
	v_exp_f32_e32 v92, v94
	v_exp_f32_e32 v94, v99
	v_exp_f32_e32 v93, v95
	v_exp_f32_e32 v95, v98
	v_cndmask_b32_e64 v112, v96, 1.0, s[52:53]
	v_pk_add_f32 v[96:97], v[86:87], v[84:85]
	v_pk_add_f32 v[98:99], v[74:75], v[66:67]
	v_pk_add_f32 v[100:101], v[94:95], v[92:93]
	v_pk_add_f32 v[102:103], v[78:79], v[70:71]
	v_pk_add_f32 v[104:105], v[82:83], v[80:81]
	v_pk_add_f32 v[106:107], v[72:73], v[64:65]
	v_pk_add_f32 v[108:109], v[90:91], v[88:89]
	v_pk_add_f32 v[110:111], v[76:77], v[68:69]
	v_pk_add_f32 v[104:105], v[106:107], v[104:105]
	v_pk_add_f32 v[108:109], v[110:111], v[108:109]
	v_pk_add_f32 v[100:101], v[102:103], v[100:101]
	v_pk_add_f32 v[96:97], v[98:99], v[96:97]
	v_pk_add_f32 v[98:99], v[104:105], v[108:109]
	v_pk_add_f32 v[96:97], v[96:97], v[100:101]
	v_add_f32_e32 v98, v98, v99
	v_add_f32_e32 v96, v96, v97
	v_add_f32_e32 v96, v98, v96
	v_fmac_f32_e32 v96, v157, v112
	v_add_u32_e32 v252, s6, v198
	v_add_u32_e32 v253, s6, v202
	v_add_u32_e32 v254, s6, v203
	v_add_u32_e32 v255, s6, v204
	ds_read_b128 v[208:211], v252 offset:24576
	ds_read_b128 v[214:217], v252 offset:28672
	ds_read_b128 v[218:221], v252 offset:32768
	ds_read_b128 v[222:225], v252 offset:36864
	ds_read_b128 v[244:247], v253 offset:24576
	ds_read_b128 v[248:251], v253 offset:28672
	v_cvt_pk_bf16_f32 v64, v64, v65
	v_cvt_pk_bf16_f32 v65, v66, v67
	v_cvt_pk_bf16_f32 v66, v68, v69
	v_cvt_pk_bf16_f32 v67, v70, v71
	s_nop 0
	s_waitcnt lgkmcnt(5)
	v_mfma_f32_32x32x16_bf16 v[48:63], v[208:211], v[64:67], v[48:63]
	ds_read_b128 v[208:211], v253 offset:32768
	s_waitcnt lgkmcnt(5)
	v_mfma_f32_32x32x16_bf16 v[32:47], v[214:217], v[64:67], v[32:47]
	ds_read_b128 v[214:217], v253 offset:36864
	s_waitcnt lgkmcnt(5)
	v_mfma_f32_32x32x16_bf16 v[16:31], v[218:221], v[64:67], v[16:31]
	ds_read_b128 v[218:221], v254 offset:24576
	s_waitcnt lgkmcnt(5)
	v_mfma_f32_32x32x16_bf16 v[0:15], v[222:225], v[64:67], v[0:15]
	ds_read_b128 v[222:225], v254 offset:28672
	s_nop 0
	v_cvt_pk_bf16_f32 v64, v80, v81
	v_cvt_pk_bf16_f32 v65, v84, v85
	v_cvt_pk_bf16_f32 v66, v88, v89
	v_cvt_pk_bf16_f32 v67, v92, v93
	s_nop 0
	s_waitcnt lgkmcnt(5)
	v_mfma_f32_32x32x16_bf16 v[48:63], v[244:247], v[64:67], v[48:63]
	ds_read_b128 v[244:247], v254 offset:32768
	s_waitcnt lgkmcnt(5)
	v_mfma_f32_32x32x16_bf16 v[32:47], v[248:251], v[64:67], v[32:47]
	ds_read_b128 v[248:251], v254 offset:36864
	s_waitcnt lgkmcnt(5)
	v_mfma_f32_32x32x16_bf16 v[16:31], v[208:211], v[64:67], v[16:31]
	ds_read_b128 v[208:211], v255 offset:24576
	s_waitcnt lgkmcnt(5)
	v_mfma_f32_32x32x16_bf16 v[0:15], v[214:217], v[64:67], v[0:15]
	ds_read_b128 v[214:217], v255 offset:28672
	s_nop 0
	v_cvt_pk_bf16_f32 v64, v72, v73
	v_cvt_pk_bf16_f32 v65, v74, v75
	v_cvt_pk_bf16_f32 v66, v76, v77
	v_cvt_pk_bf16_f32 v67, v78, v79
	s_nop 0
	s_waitcnt lgkmcnt(5)
	v_mfma_f32_32x32x16_bf16 v[48:63], v[218:221], v[64:67], v[48:63]
	ds_read_b128 v[218:221], v255 offset:32768
	s_waitcnt lgkmcnt(5)
	v_mfma_f32_32x32x16_bf16 v[32:47], v[222:225], v[64:67], v[32:47]
	ds_read_b128 v[222:225], v255 offset:36864
	s_waitcnt lgkmcnt(5)
	v_mfma_f32_32x32x16_bf16 v[16:31], v[244:247], v[64:67], v[16:31]
	s_waitcnt lgkmcnt(4)
	v_mfma_f32_32x32x16_bf16 v[0:15], v[248:251], v[64:67], v[0:15]
	s_nop 0
	v_cvt_pk_bf16_f32 v64, v82, v83
	v_cvt_pk_bf16_f32 v65, v86, v87
	v_cvt_pk_bf16_f32 v66, v90, v91
	v_cvt_pk_bf16_f32 v67, v94, v95
	s_nop 0
	s_waitcnt lgkmcnt(3)
	v_mfma_f32_32x32x16_bf16 v[48:63], v[208:211], v[64:67], v[48:63]
	s_waitcnt lgkmcnt(2)
	v_mfma_f32_32x32x16_bf16 v[32:47], v[214:217], v[64:67], v[32:47]
	s_waitcnt lgkmcnt(1)
	v_mfma_f32_32x32x16_bf16 v[16:31], v[218:221], v[64:67], v[16:31]
	s_waitcnt lgkmcnt(0)
	v_mfma_f32_32x32x16_bf16 v[0:15], v[222:225], v[64:67], v[0:15]
	s_nop 0
	v_mov_b32_e32 v157, v96

; #define LAS __attribute__((address_space(3)))
; __device__ __forceinline__ void attn_meta(LAS unsigned char* lds, const bf16_t* Q, const bf16_t* KN, const bf16_t* KPE, const bf16_t* VT, bf16_t* Y, float* ssq_b, int b, int h) {
;     const int tid = threadIdx.x; LAS float* sc = (LAS float*)lds;
;     if (tid < 256) {
;         const int qi = tid >> 7, k = (tid >> 3) & 15, part = tid & 7;
;         const size_t qrow = (size_t)16384 + 14 + qi, krow = (size_t)16384 + k; float acc = 0.f;
; #pragma unroll
;         for (int i = 0; i < 3; ++i) { const int pc = part * 3 + i;
;             const u32x4 qw = *(const u32x4*)(Q + qrow * 1536 + h * 192 + pc * 8);
;             const u32x4 kw = pc < 16 ? *(const u32x4*)(KN + krow * 1024 + h * 128 + pc * 8) : *(const u32x4*)(KPE + krow * 64 + (pc - 16) * 8);
;             acc += dot8(qw, kw); }
;         acc += __shfl_xor(acc, 1); acc += __shfl_xor(acc, 2); acc += __shfl_xor(acc, 4);
;         if (part == 0) sc[qi * 16 + k] = acc;
.LBB0_708:
	s_setprio 0
	v_readlane_b32 s28, v242, 30
	s_cmp_gt_i32 s2, 7
	v_readlane_b32 s29, v242, 31
	s_cbranch_scc1 .LBB0_717
	v_bfe_u32 v6, v170, 3, 4
	v_mul_u32_u24_e32 v0, 0x600, v175
	v_or_b32_e32 v4, 0x4000, v6
	v_lshlrev_b32_e32 v0, 1, v0
	s_waitcnt lgkmcnt(0)
	v_mov_b32_e32 v1, 0
	v_lshl_add_u64 v[10:11], s[60:61], 0, v[0:1]
	v_lshlrev_b32_e32 v0, 7, v4
	v_and_b32_e32 v7, 7, v170
	v_lshl_add_u64 v[2:3], s[14:15], 0, v[0:1]
	v_lshlrev_b32_e32 v0, 11, v4
	v_lshl_add_u64 v[12:13], s[4:5], 0, v[0:1]
	v_mul_u32_u24_e32 v0, 24, v7
	v_lshlrev_b32_e32 v0, 1, v0
	s_movk_i32 s4, 0xff00
	v_lshl_add_u64 v[4:5], v[2:3], 0, v[0:1]
	s_mov_b32 s5, -1
	v_lshl_add_u32 v16, v175, 6, 0
	v_or_b32_e32 v14, 0x4000, v175
	v_cmp_gt_u32_e64 s[52:53], 6, v7
	v_lshl_add_u64 v[2:3], v[4:5], 0, s[4:5]
	v_cmp_gt_u32_e64 s[54:55], 5, v7
	s_movk_i32 s4, 0xff10
	v_cmp_eq_u32_e64 s[56:57], 0, v7
	v_lshl_add_u32 v17, v6, 2, v16
	v_lshlrev_b32_e32 v6, 12, v14
	v_mov_b32_e32 v7, v1
	s_mov_b32 s5, -1
	v_lshl_add_u64 v[6:7], s[58:59], 0, v[6:7]
	v_lshlrev_b32_e32 v8, 1, v147
	v_mov_b32_e32 v9, v1
	v_mbcnt_hi_u32_b32 v18, -1, v212
	v_lshl_add_u64 v[4:5], v[4:5], 0, s[4:5]
	v_lshl_add_u64 v[6:7], v[6:7], 0, v[8:9]
	v_lshlrev_b32_e32 v8, 2, v14
	v_lshl_add_u64 v[10:11], v[10:11], 0, v[0:1]
	s_mov_b64 s[4:5], 0x300a800
	v_and_b32_e32 v14, 64, v18
	v_lshl_add_u64 v[8:9], s[62:63], 0, v[8:9]
	v_lshl_add_u64 v[10:11], v[10:11], 0, s[4:5]
	v_lshl_add_u64 v[12:13], v[12:13], 0, v[0:1]
	v_or_b32_e32 v0, 0x2000, v147
	s_lshl_b32 s4, s2, 7
	s_mul_i32 s6, s2, 0xc0
	v_xor_b32_e32 v19, 1, v18
	v_add_u32_e32 v20, 64, v14
	v_xor_b32_e32 v21, 2, v18
	v_xor_b32_e32 v22, 4, v18
	s_mov_b32 s8, s2
	s_branch .LBB0_711
